# k28 + loop-edge rotation: back-edge SALU of the six GEMM K loops moved above the closing barrier into the last MFMA cluster
# baseline (speedup 1.0000x reference)
; #define PG8_STAGE(bufoff, gbase, voff) do { _Pragma("unroll") for (int _i = 0; _i < 2; ++_i) \
;         __builtin_amdgcn_global_load_lds((const unsigned*)((const char*)(gbase) + (voff)[_i]), (PG8_LAS unsigned*)(lds + (bufoff) + ldsw + _i * 8192), 16, 0, 0); } while (0)
; #define PG8_LDA(dst, b, h) do { _Pragma("unroll") for (int m = 0; m < 4; ++m) _Pragma("unroll") for (int k = 0; k < 2; ++k) dst[m][k] = *(const PG8_LAS bf16x8*)(lds + PG8_SA(b, h) + aoff + m * 2048 + k * 1024); } while (0)
; #define PG8_LDB(dst, b, h) do { _Pragma("unroll") for (int n = 0; n < 2; ++n) _Pragma("unroll") for (int k = 0; k < 2; ++k) dst[n][k] = *(const PG8_LAS bf16x8*)(lds + PG8_SB(b, h) + boff + n * 2048 + k * 1024); } while (0)
; #define PG8_MMA(ai, bj, At, Bt) do { __builtin_amdgcn_s_setprio(1); _Pragma("unroll") for (int m = 0; m < 4; ++m) _Pragma("unroll") for (int n = 0; n < 2; ++n) _Pragma("unroll") for (int k = 0; k < 2; ++k) \
;         acc[ai][bj][m][n] = __builtin_amdgcn_mfma_f32_16x16x32_bf16(Bt[n][k], At[m][k], acc[ai][bj][m][n], 0, 0, 0); __builtin_amdgcn_s_setprio(0); } while (0)
; #define PG8_WAIT_V(n) asm volatile("s_waitcnt vmcnt(" #n ")" ::: "memory")
; #define PG8_WAIT_L(n) asm volatile("s_waitcnt lgkmcnt(" #n ")" ::: "memory")
; #define PG8_BAR __builtin_amdgcn_s_barrier()
; #define PG8_SCHED __builtin_amdgcn_sched_barrier(0)
; template <class Epi>
; __device__ __forceinline__ void gemm_phase(PG8_LAS unsigned char* lds, const Gemm g, const StaticOrder& S, const Epi& E, const int wave_s) {
;     ...
;         for (int t = 0; t < nt; t += 2) {
;             const bool last = (t == nt - 2);
;             const char* a1 = cA + (size_t)(t + 1) * kstep;
;             const char* a2 = last ? nA : cA + (size_t)(t + 2) * kstep; const char* b2 = last ? nB : cB + (size_t)(t + 2) * kstep;
;             const char* a3 = a2 + kstep; const char* b3 = b2 + kstep;
;             PG8_LDB(B0, 0, 0); PG8_LDB(B1, 0, 1); PG8_SCHED; PG8_LDA(At, 0, 0); PG8_STAGE(PG8_SA(1, 1), a1 + hstepA, voffA);
;             PG8_WAIT_V(8); PG8_WAIT_L(0); PG8_BAR; PG8_MMA(0, 0, At, B0); PG8_MMA(0, 1, At, B1); PG8_BAR; PG8_SCHED;
;             PG8_LDA(At, 0, 1); PG8_STAGE(PG8_SB(0, 0), b2, voffB); PG8_STAGE(PG8_SB(0, 1), b2 + hstepB, voffB); PG8_STAGE(PG8_SA(0, 0), a2, voffA);
;             PG8_WAIT_V(8); PG8_WAIT_L(0); PG8_BAR; PG8_MMA(1, 0, At, B0); PG8_MMA(1, 1, At, B1); PG8_BAR; PG8_SCHED;
.Lg0_prio_done:
.LBB0_131:
	s_add_i32 s46, s6, 2
	s_add_u32 s47, s44, 0x80
	s_addc_u32 s7, s45, 0
	s_add_i32 s61, 0, 0x10000
	s_cmp_eq_u32 s40, s6
	s_cselect_b32 s7, s91, s7
	s_cselect_b32 s6, s90, s47
	s_cselect_b32 s73, s93, s13
	s_cselect_b32 s72, s92, s12
	s_add_i32 s47, 0, 0x14000
	v_add_u32_e32 v142, s61, v97
	v_add_u32_e32 v158, s47, v97
	ds_read_b128 v[130:133], v142
	ds_read_b128 v[134:137], v142 offset:1024
	ds_read_b128 v[138:141], v142 offset:2048
	ds_read_b128 v[142:145], v142 offset:3072
	ds_read_b128 v[146:149], v158
	ds_read_b128 v[150:153], v158 offset:1024
	ds_read_b128 v[154:157], v158 offset:2048
	ds_read_b128 v[158:161], v158 offset:3072
	v_lshl_add_u64 v[194:195], s[44:45], 0, v[224:225]
	s_add_i32 m0, s9, 0xc000
	ds_read_b128 v[162:165], v232
	ds_read_b128 v[166:169], v232 offset:1024
	ds_read_b128 v[170:173], v232 offset:2048
	ds_read_b128 v[174:177], v232 offset:3072
	ds_read_b128 v[178:181], v232 offset:4096
	ds_read_b128 v[182:185], v232 offset:5120
	ds_read_b128 v[186:189], v232 offset:6144
	ds_read_b128 v[190:193], v232 offset:7168
	global_load_lds_dwordx4 v[194:195], off
	v_lshl_add_u64 v[194:195], s[44:45], 0, v[226:227]
	s_add_i32 m0, s9, 0xe000
	s_nop 0
	global_load_lds_dwordx4 v[194:195], off
	s_waitcnt vmcnt(8)
	s_waitcnt lgkmcnt(0)
	s_barrier
	s_waitcnt lgkmcnt(0)
	v_mfma_f32_16x16x32_bf16 v[126:129], v[130:133], v[162:165], v[126:129]
	v_mfma_f32_16x16x32_bf16 v[122:125], v[138:141], v[162:165], v[122:125]
	v_mfma_f32_16x16x32_bf16 v[110:113], v[130:133], v[170:173], v[110:113]
	v_mfma_f32_16x16x32_bf16 v[106:109], v[138:141], v[170:173], v[106:109]
	v_mfma_f32_16x16x32_bf16 v[92:95], v[130:133], v[178:181], v[92:95]
	v_mfma_f32_16x16x32_bf16 v[88:91], v[138:141], v[178:181], v[88:91]
	v_mfma_f32_16x16x32_bf16 v[76:79], v[130:133], v[186:189], v[76:79]
	v_mfma_f32_16x16x32_bf16 v[72:75], v[138:141], v[186:189], v[72:75]
	v_mfma_f32_16x16x32_bf16 v[126:129], v[134:137], v[166:169], v[126:129]
	v_mfma_f32_16x16x32_bf16 v[122:125], v[142:145], v[166:169], v[122:125]
	v_mfma_f32_16x16x32_bf16 v[110:113], v[134:137], v[174:177], v[110:113]
	v_mfma_f32_16x16x32_bf16 v[106:109], v[142:145], v[174:177], v[106:109]
	v_mfma_f32_16x16x32_bf16 v[92:95], v[134:137], v[182:185], v[92:95]
	v_mfma_f32_16x16x32_bf16 v[88:91], v[142:145], v[182:185], v[88:91]
	v_mfma_f32_16x16x32_bf16 v[76:79], v[134:137], v[190:193], v[76:79]
	v_mfma_f32_16x16x32_bf16 v[72:75], v[142:145], v[190:193], v[72:75]
	v_mfma_f32_16x16x32_bf16 v[118:121], v[146:149], v[162:165], v[118:121]
	v_mfma_f32_16x16x32_bf16 v[114:117], v[154:157], v[162:165], v[114:117]
	v_mfma_f32_16x16x32_bf16 v[102:105], v[146:149], v[170:173], v[102:105]
	v_mfma_f32_16x16x32_bf16 v[98:101], v[154:157], v[170:173], v[98:101]
	v_mfma_f32_16x16x32_bf16 v[84:87], v[146:149], v[178:181], v[84:87]
	v_mfma_f32_16x16x32_bf16 v[80:83], v[154:157], v[178:181], v[80:83]
	v_mfma_f32_16x16x32_bf16 v[68:71], v[146:149], v[186:189], v[68:71]
	v_mfma_f32_16x16x32_bf16 v[64:67], v[154:157], v[186:189], v[64:67]
	v_mfma_f32_16x16x32_bf16 v[118:121], v[150:153], v[166:169], v[118:121]
	v_mfma_f32_16x16x32_bf16 v[114:117], v[158:161], v[166:169], v[114:117]
	v_mfma_f32_16x16x32_bf16 v[102:105], v[150:153], v[174:177], v[102:105]
	v_mfma_f32_16x16x32_bf16 v[98:101], v[158:161], v[174:177], v[98:101]
	v_mfma_f32_16x16x32_bf16 v[84:87], v[150:153], v[182:185], v[84:87]
	v_mfma_f32_16x16x32_bf16 v[80:83], v[158:161], v[182:185], v[80:83]
	v_mfma_f32_16x16x32_bf16 v[68:71], v[150:153], v[190:193], v[68:71]
	v_mfma_f32_16x16x32_bf16 v[64:67], v[158:161], v[190:193], v[64:67]
	s_barrier
	s_add_i32 s61, s61, s5
	v_lshl_add_u64 v[194:195], s[72:73], 0, v[210:211]
	s_mov_b32 m0, s61
	ds_read_b128 v[162:165], v232 offset:16384
	ds_read_b128 v[166:169], v232 offset:17408
	ds_read_b128 v[170:173], v232 offset:18432
	ds_read_b128 v[174:177], v232 offset:19456
	ds_read_b128 v[178:181], v232 offset:20480
	ds_read_b128 v[182:185], v232 offset:21504
	ds_read_b128 v[186:189], v232 offset:22528
	ds_read_b128 v[190:193], v232 offset:23552
	global_load_lds_dwordx4 v[194:195], off
	s_add_i32 m0, s61, 0x2000
	v_lshl_add_u64 v[196:197], s[72:73], 0, v[222:223]
	s_add_u32 s72, s72, s50
	s_addc_u32 s73, s73, s51
	s_add_i32 s47, s47, s5
	global_load_lds_dwordx4 v[196:197], off
	v_lshl_add_u64 v[198:199], s[72:73], 0, v[210:211]
	s_mov_b32 m0, s47
	v_lshl_add_u64 v[200:201], s[72:73], 0, v[222:223]
	global_load_lds_dwordx4 v[198:199], off
	s_add_i32 m0, s47, 0x2000
	v_lshl_add_u64 v[202:203], s[6:7], 0, v[218:219]
	global_load_lds_dwordx4 v[200:201], off
	s_mov_b32 m0, s9
	v_lshl_add_u64 v[204:205], s[6:7], 0, v[220:221]
	global_load_lds_dwordx4 v[202:203], off
	s_mov_b32 m0, s10
	s_nop 0
	global_load_lds_dwordx4 v[204:205], off
	s_waitcnt vmcnt(8)
	s_waitcnt lgkmcnt(0)
	s_barrier
; #define PG8_STAGE(bufoff, gbase, voff) do { _Pragma("unroll") for (int _i = 0; _i < 2; ++_i) \
;         __builtin_amdgcn_global_load_lds((const unsigned*)((const char*)(gbase) + (voff)[_i]), (PG8_LAS unsigned*)(lds + (bufoff) + ldsw + _i * 8192), 16, 0, 0); } while (0)
; #define PG8_LDA(dst, b, h) do { _Pragma("unroll") for (int m = 0; m < 4; ++m) _Pragma("unroll") for (int k = 0; k < 2; ++k) dst[m][k] = *(const PG8_LAS bf16x8*)(lds + PG8_SA(b, h) + aoff + m * 2048 + k * 1024); } while (0)
; #define PG8_LDB(dst, b, h) do { _Pragma("unroll") for (int n = 0; n < 2; ++n) _Pragma("unroll") for (int k = 0; k < 2; ++k) dst[n][k] = *(const PG8_LAS bf16x8*)(lds + PG8_SB(b, h) + boff + n * 2048 + k * 1024); } while (0)
; #define PG8_MMA(ai, bj, At, Bt) do { __builtin_amdgcn_s_setprio(1); _Pragma("unroll") for (int m = 0; m < 4; ++m) _Pragma("unroll") for (int n = 0; n < 2; ++n) _Pragma("unroll") for (int k = 0; k < 2; ++k) \
;         acc[ai][bj][m][n] = __builtin_amdgcn_mfma_f32_16x16x32_bf16(Bt[n][k], At[m][k], acc[ai][bj][m][n], 0, 0, 0); __builtin_amdgcn_s_setprio(0); } while (0)
; #define PG8_WAIT_V(n) asm volatile("s_waitcnt vmcnt(" #n ")" ::: "memory")
; #define PG8_WAIT_L(n) asm volatile("s_waitcnt lgkmcnt(" #n ")" ::: "memory")
; #define PG8_BAR __builtin_amdgcn_s_barrier()
; #define PG8_SCHED __builtin_amdgcn_sched_barrier(0)
; template <class Epi>
; __device__ __forceinline__ void gemm_phase(PG8_LAS unsigned char* lds, const Gemm g, const StaticOrder& S, const Epi& E, const int wave_s) {
;     ...
;             PG8_WAIT_V(8); PG8_WAIT_L(0); PG8_BAR; PG8_MMA(1, 0, At, B0); PG8_MMA(1, 1, At, B1); PG8_BAR; PG8_SCHED;
;             PG8_LDB(B0, 1, 0); PG8_LDB(B1, 1, 1); PG8_SCHED; PG8_LDA(At, 1, 0); PG8_STAGE(PG8_SA(0, 1), a2 + hstepA, voffA);
;             PG8_WAIT_V(8); PG8_WAIT_L(0); PG8_BAR; PG8_MMA(0, 0, At, B0); PG8_MMA(0, 1, At, B1); PG8_BAR; PG8_SCHED;
	s_waitcnt lgkmcnt(0)
	v_mfma_f32_16x16x32_bf16 v[60:63], v[130:133], v[162:165], v[60:63]
	v_mfma_f32_16x16x32_bf16 v[56:59], v[138:141], v[162:165], v[56:59]
	v_mfma_f32_16x16x32_bf16 v[44:47], v[130:133], v[170:173], v[44:47]
	v_mfma_f32_16x16x32_bf16 v[40:43], v[138:141], v[170:173], v[40:43]
	v_mfma_f32_16x16x32_bf16 v[28:31], v[130:133], v[178:181], v[28:31]
	v_mfma_f32_16x16x32_bf16 v[24:27], v[138:141], v[178:181], v[24:27]
	v_mfma_f32_16x16x32_bf16 v[12:15], v[130:133], v[186:189], v[12:15]
	v_mfma_f32_16x16x32_bf16 v[8:11], v[138:141], v[186:189], v[8:11]
	v_mfma_f32_16x16x32_bf16 v[60:63], v[134:137], v[166:169], v[60:63]
	v_mfma_f32_16x16x32_bf16 v[56:59], v[142:145], v[166:169], v[56:59]
	v_mfma_f32_16x16x32_bf16 v[44:47], v[134:137], v[174:177], v[44:47]
	v_mfma_f32_16x16x32_bf16 v[40:43], v[142:145], v[174:177], v[40:43]
	v_mfma_f32_16x16x32_bf16 v[28:31], v[134:137], v[182:185], v[28:31]
	v_mfma_f32_16x16x32_bf16 v[24:27], v[142:145], v[182:185], v[24:27]
	v_mfma_f32_16x16x32_bf16 v[12:15], v[134:137], v[190:193], v[12:15]
	v_mfma_f32_16x16x32_bf16 v[8:11], v[142:145], v[190:193], v[8:11]
	v_mfma_f32_16x16x32_bf16 v[52:55], v[146:149], v[162:165], v[52:55]
	v_mfma_f32_16x16x32_bf16 v[48:51], v[154:157], v[162:165], v[48:51]
	v_mfma_f32_16x16x32_bf16 v[36:39], v[146:149], v[170:173], v[36:39]
	v_mfma_f32_16x16x32_bf16 v[32:35], v[154:157], v[170:173], v[32:35]
	v_mfma_f32_16x16x32_bf16 v[20:23], v[146:149], v[178:181], v[20:23]
	v_mfma_f32_16x16x32_bf16 v[16:19], v[154:157], v[178:181], v[16:19]
	v_mfma_f32_16x16x32_bf16 v[4:7], v[146:149], v[186:189], v[4:7]
	v_mfma_f32_16x16x32_bf16 v[0:3], v[154:157], v[186:189], v[0:3]
	v_mfma_f32_16x16x32_bf16 v[52:55], v[150:153], v[166:169], v[52:55]
	v_mfma_f32_16x16x32_bf16 v[48:51], v[158:161], v[166:169], v[48:51]
	v_mfma_f32_16x16x32_bf16 v[36:39], v[150:153], v[174:177], v[36:39]
	v_mfma_f32_16x16x32_bf16 v[32:35], v[158:161], v[174:177], v[32:35]
	v_mfma_f32_16x16x32_bf16 v[20:23], v[150:153], v[182:185], v[20:23]
	v_mfma_f32_16x16x32_bf16 v[16:19], v[158:161], v[182:185], v[16:19]
	v_mfma_f32_16x16x32_bf16 v[4:7], v[150:153], v[190:193], v[4:7]
	v_mfma_f32_16x16x32_bf16 v[0:3], v[158:161], v[190:193], v[0:3]
	s_barrier
	s_add_i32 s47, 0, 0x18000
	s_add_i32 s61, 0, 0x1c000
	v_add_u32_e32 v142, s47, v97
	v_add_u32_e32 v158, s61, v97
	ds_read_b128 v[130:133], v142
	ds_read_b128 v[134:137], v142 offset:1024
	ds_read_b128 v[138:141], v142 offset:2048
	ds_read_b128 v[142:145], v142 offset:3072
	ds_read_b128 v[146:149], v158
	ds_read_b128 v[150:153], v158 offset:1024
	ds_read_b128 v[154:157], v158 offset:2048
	ds_read_b128 v[158:161], v158 offset:3072
	s_add_u32 s6, s6, s48
	s_addc_u32 s7, s7, s49
	s_mov_b32 m0, s11
	v_lshl_add_u64 v[206:207], s[6:7], 0, v[218:219]
	ds_read_b128 v[162:165], v232 offset:32768
	ds_read_b128 v[166:169], v232 offset:33792
	ds_read_b128 v[170:173], v232 offset:34816
	ds_read_b128 v[174:177], v232 offset:35840
	ds_read_b128 v[178:181], v232 offset:36864
	ds_read_b128 v[182:185], v232 offset:37888
	ds_read_b128 v[186:189], v232 offset:38912
	ds_read_b128 v[190:193], v232 offset:39936
	global_load_lds_dwordx4 v[206:207], off
	v_lshl_add_u64 v[206:207], s[6:7], 0, v[220:221]
	s_mov_b32 m0, s16
	s_nop 0
	global_load_lds_dwordx4 v[206:207], off
	s_waitcnt vmcnt(8)
	s_waitcnt lgkmcnt(0)
	s_barrier
	s_waitcnt lgkmcnt(0)
	v_mfma_f32_16x16x32_bf16 v[126:129], v[130:133], v[162:165], v[126:129]
	v_mfma_f32_16x16x32_bf16 v[122:125], v[138:141], v[162:165], v[122:125]
	v_mfma_f32_16x16x32_bf16 v[110:113], v[130:133], v[170:173], v[110:113]
	v_mfma_f32_16x16x32_bf16 v[106:109], v[138:141], v[170:173], v[106:109]
	v_mfma_f32_16x16x32_bf16 v[92:95], v[130:133], v[178:181], v[92:95]
	v_mfma_f32_16x16x32_bf16 v[88:91], v[138:141], v[178:181], v[88:91]
	v_mfma_f32_16x16x32_bf16 v[76:79], v[130:133], v[186:189], v[76:79]
	v_mfma_f32_16x16x32_bf16 v[72:75], v[138:141], v[186:189], v[72:75]
	v_mfma_f32_16x16x32_bf16 v[126:129], v[134:137], v[166:169], v[126:129]
	v_mfma_f32_16x16x32_bf16 v[122:125], v[142:145], v[166:169], v[122:125]
	v_mfma_f32_16x16x32_bf16 v[110:113], v[134:137], v[174:177], v[110:113]
	v_mfma_f32_16x16x32_bf16 v[106:109], v[142:145], v[174:177], v[106:109]
	v_mfma_f32_16x16x32_bf16 v[92:95], v[134:137], v[182:185], v[92:95]
	v_mfma_f32_16x16x32_bf16 v[88:91], v[142:145], v[182:185], v[88:91]
	v_mfma_f32_16x16x32_bf16 v[76:79], v[134:137], v[190:193], v[76:79]
	v_mfma_f32_16x16x32_bf16 v[72:75], v[142:145], v[190:193], v[72:75]
	v_mfma_f32_16x16x32_bf16 v[118:121], v[146:149], v[162:165], v[118:121]
	v_mfma_f32_16x16x32_bf16 v[114:117], v[154:157], v[162:165], v[114:117]
	v_mfma_f32_16x16x32_bf16 v[102:105], v[146:149], v[170:173], v[102:105]
	v_mfma_f32_16x16x32_bf16 v[98:101], v[154:157], v[170:173], v[98:101]
	v_mfma_f32_16x16x32_bf16 v[84:87], v[146:149], v[178:181], v[84:87]
	v_mfma_f32_16x16x32_bf16 v[80:83], v[154:157], v[178:181], v[80:83]
	v_mfma_f32_16x16x32_bf16 v[68:71], v[146:149], v[186:189], v[68:71]
	v_mfma_f32_16x16x32_bf16 v[64:67], v[154:157], v[186:189], v[64:67]
	v_mfma_f32_16x16x32_bf16 v[118:121], v[150:153], v[166:169], v[118:121]
	v_mfma_f32_16x16x32_bf16 v[114:117], v[158:161], v[166:169], v[114:117]
	v_mfma_f32_16x16x32_bf16 v[102:105], v[150:153], v[174:177], v[102:105]
	v_mfma_f32_16x16x32_bf16 v[98:101], v[158:161], v[174:177], v[98:101]
	v_mfma_f32_16x16x32_bf16 v[84:87], v[150:153], v[182:185], v[84:87]
	v_mfma_f32_16x16x32_bf16 v[80:83], v[158:161], v[182:185], v[80:83]
	v_mfma_f32_16x16x32_bf16 v[68:71], v[150:153], v[190:193], v[68:71]
	v_mfma_f32_16x16x32_bf16 v[64:67], v[158:161], v[190:193], v[64:67]
	s_barrier
; #define PG8_STAGE(bufoff, gbase, voff) do { _Pragma("unroll") for (int _i = 0; _i < 2; ++_i) \
;         __builtin_amdgcn_global_load_lds((const unsigned*)((const char*)(gbase) + (voff)[_i]), (PG8_LAS unsigned*)(lds + (bufoff) + ldsw + _i * 8192), 16, 0, 0); } while (0)
; #define PG8_LDA(dst, b, h) do { _Pragma("unroll") for (int m = 0; m < 4; ++m) _Pragma("unroll") for (int k = 0; k < 2; ++k) dst[m][k] = *(const PG8_LAS bf16x8*)(lds + PG8_SA(b, h) + aoff + m * 2048 + k * 1024); } while (0)
; #define PG8_MMA(ai, bj, At, Bt) do { __builtin_amdgcn_s_setprio(1); _Pragma("unroll") for (int m = 0; m < 4; ++m) _Pragma("unroll") for (int n = 0; n < 2; ++n) _Pragma("unroll") for (int k = 0; k < 2; ++k) \
;         acc[ai][bj][m][n] = __builtin_amdgcn_mfma_f32_16x16x32_bf16(Bt[n][k], At[m][k], acc[ai][bj][m][n], 0, 0, 0); __builtin_amdgcn_s_setprio(0); } while (0)
; #define PG8_WAIT_V(n) asm volatile("s_waitcnt vmcnt(" #n ")" ::: "memory")
; #define PG8_WAIT_L(n) asm volatile("s_waitcnt lgkmcnt(" #n ")" ::: "memory")
; #define PG8_BAR __builtin_amdgcn_s_barrier()
; #define PG8_SCHED __builtin_amdgcn_sched_barrier(0)
; template <class Epi>
; __device__ __forceinline__ void gemm_phase(PG8_LAS unsigned char* lds, const Gemm g, const StaticOrder& S, const Epi& E, const int wave_s) {
;     ...
;             PG8_LDA(At, 1, 1); PG8_STAGE(PG8_SB(1, 0), b3, voffB); PG8_STAGE(PG8_SB(1, 1), b3 + hstepB, voffB); PG8_STAGE(PG8_SA(1, 0), a3, voffA);
;             PG8_WAIT_V(8); PG8_WAIT_L(0); PG8_BAR; PG8_MMA(1, 0, At, B0); PG8_MMA(1, 1, At, B1); PG8_BAR; PG8_SCHED;
;         }
	s_add_i32 s6, s47, s5
	v_lshl_add_u64 v[194:195], v[194:195], 0, s[52:53]
	s_mov_b32 m0, s6
	ds_read_b128 v[162:165], v232 offset:49152
	ds_read_b128 v[166:169], v232 offset:50176
	ds_read_b128 v[170:173], v232 offset:51200
	ds_read_b128 v[174:177], v232 offset:52224
	ds_read_b128 v[178:181], v232 offset:53248
	ds_read_b128 v[182:185], v232 offset:54272
	ds_read_b128 v[186:189], v232 offset:55296
	ds_read_b128 v[190:193], v232 offset:56320
	global_load_lds_dwordx4 v[194:195], off
	v_lshl_add_u64 v[194:195], v[196:197], 0, s[52:53]
	s_add_i32 m0, s6, 0x2000
	s_add_i32 s6, s61, s5
	global_load_lds_dwordx4 v[194:195], off
	v_lshl_add_u64 v[194:195], v[198:199], 0, s[52:53]
	s_mov_b32 m0, s6
	s_nop 0
	global_load_lds_dwordx4 v[194:195], off
	v_lshl_add_u64 v[194:195], v[200:201], 0, s[52:53]
	s_add_i32 m0, s6, 0x2000
	s_nop 0
	global_load_lds_dwordx4 v[194:195], off
	v_lshl_add_u64 v[194:195], v[202:203], 0, s[52:53]
	s_mov_b32 m0, s38
	s_nop 0
	global_load_lds_dwordx4 v[194:195], off
	v_lshl_add_u64 v[194:195], v[204:205], 0, s[52:53]
	s_mov_b32 m0, s39
	s_nop 0
	global_load_lds_dwordx4 v[194:195], off
	s_waitcnt vmcnt(8)
	s_waitcnt lgkmcnt(0)
	s_barrier
	s_waitcnt lgkmcnt(0)
	v_mfma_f32_16x16x32_bf16 v[60:63], v[130:133], v[162:165], v[60:63]
	v_mfma_f32_16x16x32_bf16 v[56:59], v[138:141], v[162:165], v[56:59]
	s_add_u32 s44, s44, 0x100
	s_addc_u32 s45, s45, 0
	s_add_u32 s12, s12, 0x100
	s_addc_u32 s13, s13, 0
	s_mov_b32 s6, s46
	s_cmp_ge_i32 s46, s37
	v_mfma_f32_16x16x32_bf16 v[44:47], v[130:133], v[170:173], v[44:47]
	v_mfma_f32_16x16x32_bf16 v[40:43], v[138:141], v[170:173], v[40:43]
	v_mfma_f32_16x16x32_bf16 v[28:31], v[130:133], v[178:181], v[28:31]
	v_mfma_f32_16x16x32_bf16 v[24:27], v[138:141], v[178:181], v[24:27]
	v_mfma_f32_16x16x32_bf16 v[12:15], v[130:133], v[186:189], v[12:15]
	v_mfma_f32_16x16x32_bf16 v[8:11], v[138:141], v[186:189], v[8:11]
	v_mfma_f32_16x16x32_bf16 v[60:63], v[134:137], v[166:169], v[60:63]
	v_mfma_f32_16x16x32_bf16 v[56:59], v[142:145], v[166:169], v[56:59]
	v_mfma_f32_16x16x32_bf16 v[44:47], v[134:137], v[174:177], v[44:47]
	v_mfma_f32_16x16x32_bf16 v[40:43], v[142:145], v[174:177], v[40:43]
	v_mfma_f32_16x16x32_bf16 v[28:31], v[134:137], v[182:185], v[28:31]
	v_mfma_f32_16x16x32_bf16 v[24:27], v[142:145], v[182:185], v[24:27]
	v_mfma_f32_16x16x32_bf16 v[12:15], v[134:137], v[190:193], v[12:15]
	v_mfma_f32_16x16x32_bf16 v[8:11], v[142:145], v[190:193], v[8:11]
	v_mfma_f32_16x16x32_bf16 v[52:55], v[146:149], v[162:165], v[52:55]
	v_mfma_f32_16x16x32_bf16 v[48:51], v[154:157], v[162:165], v[48:51]
	v_mfma_f32_16x16x32_bf16 v[36:39], v[146:149], v[170:173], v[36:39]
	v_mfma_f32_16x16x32_bf16 v[32:35], v[154:157], v[170:173], v[32:35]
	v_mfma_f32_16x16x32_bf16 v[20:23], v[146:149], v[178:181], v[20:23]
	v_mfma_f32_16x16x32_bf16 v[16:19], v[154:157], v[178:181], v[16:19]
	v_mfma_f32_16x16x32_bf16 v[4:7], v[146:149], v[186:189], v[4:7]
	v_mfma_f32_16x16x32_bf16 v[0:3], v[154:157], v[186:189], v[0:3]
	v_mfma_f32_16x16x32_bf16 v[52:55], v[150:153], v[166:169], v[52:55]
	v_mfma_f32_16x16x32_bf16 v[48:51], v[158:161], v[166:169], v[48:51]
	v_mfma_f32_16x16x32_bf16 v[36:39], v[150:153], v[174:177], v[36:39]
	v_mfma_f32_16x16x32_bf16 v[32:35], v[158:161], v[174:177], v[32:35]
	v_mfma_f32_16x16x32_bf16 v[20:23], v[150:153], v[182:185], v[20:23]
	v_mfma_f32_16x16x32_bf16 v[16:19], v[158:161], v[182:185], v[16:19]
	v_mfma_f32_16x16x32_bf16 v[4:7], v[150:153], v[190:193], v[4:7]
	v_mfma_f32_16x16x32_bf16 v[0:3], v[158:161], v[190:193], v[0:3]
	s_barrier
	s_cbranch_scc0 .LBB0_131
	s_setprio 0

; #define PG8_STAGE(bufoff, gbase, voff) do { _Pragma("unroll") for (int _i = 0; _i < 2; ++_i) \
;         __builtin_amdgcn_global_load_lds((const unsigned*)((const char*)(gbase) + (voff)[_i]), (PG8_LAS unsigned*)(lds + (bufoff) + ldsw + _i * 8192), 16, 0, 0); } while (0)
; #define PG8_LDA(dst, b, h) do { _Pragma("unroll") for (int m = 0; m < 4; ++m) _Pragma("unroll") for (int k = 0; k < 2; ++k) dst[m][k] = *(const PG8_LAS bf16x8*)(lds + PG8_SA(b, h) + aoff + m * 2048 + k * 1024); } while (0)
; #define PG8_LDB(dst, b, h) do { _Pragma("unroll") for (int n = 0; n < 2; ++n) _Pragma("unroll") for (int k = 0; k < 2; ++k) dst[n][k] = *(const PG8_LAS bf16x8*)(lds + PG8_SB(b, h) + boff + n * 2048 + k * 1024); } while (0)
; #define PG8_MMA(ai, bj, At, Bt) do { __builtin_amdgcn_s_setprio(1); _Pragma("unroll") for (int m = 0; m < 4; ++m) _Pragma("unroll") for (int n = 0; n < 2; ++n) _Pragma("unroll") for (int k = 0; k < 2; ++k) \
;         acc[ai][bj][m][n] = __builtin_amdgcn_mfma_f32_16x16x32_bf16(Bt[n][k], At[m][k], acc[ai][bj][m][n], 0, 0, 0); __builtin_amdgcn_s_setprio(0); } while (0)
; #define PG8_WAIT_V(n) asm volatile("s_waitcnt vmcnt(" #n ")" ::: "memory")
; #define PG8_WAIT_L(n) asm volatile("s_waitcnt lgkmcnt(" #n ")" ::: "memory")
; #define PG8_BAR __builtin_amdgcn_s_barrier()
; #define PG8_SCHED __builtin_amdgcn_sched_barrier(0)
; template <class Epi>
; __device__ __forceinline__ void gemm_phase(PG8_LAS unsigned char* lds, const Gemm g, const StaticOrder& S, const Epi& E, const int wave_s) {
;     ...
;         for (int t = 0; t < nt; t += 2) {
;             const bool last = (t == nt - 2);
;             const char* a1 = cA + (size_t)(t + 1) * kstep;
;             const char* a2 = last ? nA : cA + (size_t)(t + 2) * kstep; const char* b2 = last ? nB : cB + (size_t)(t + 2) * kstep;
;             const char* a3 = a2 + kstep; const char* b3 = b2 + kstep;
;             PG8_LDB(B0, 0, 0); PG8_LDB(B1, 0, 1); PG8_SCHED; PG8_LDA(At, 0, 0); PG8_STAGE(PG8_SA(1, 1), a1 + hstepA, voffA);
;             PG8_WAIT_V(8); PG8_WAIT_L(0); PG8_BAR; PG8_MMA(0, 0, At, B0); PG8_MMA(0, 1, At, B1); PG8_BAR; PG8_SCHED;
;             PG8_LDA(At, 0, 1); PG8_STAGE(PG8_SB(0, 0), b2, voffB); PG8_STAGE(PG8_SB(0, 1), b2 + hstepB, voffB); PG8_STAGE(PG8_SA(0, 0), a2, voffA);
;             PG8_WAIT_V(8); PG8_WAIT_L(0); PG8_BAR; PG8_MMA(1, 0, At, B0); PG8_MMA(1, 1, At, B1); PG8_BAR; PG8_SCHED;
.Lg1_prio_done:
.LBB0_336:
	s_add_i32 s36, s6, 2
	s_add_u32 s38, s44, 0x80
	s_addc_u32 s7, s45, 0
	s_add_i32 s46, 0, 0x10000
	s_cmp_eq_u32 s5, s6
	s_cselect_b32 s7, s91, s7
	s_cselect_b32 s6, s90, s38
	s_cselect_b32 s39, s93, s25
	s_cselect_b32 s38, s92, s9
	s_add_i32 s47, 0, 0x14000
	v_add_u32_e32 v154, s46, v97
	v_add_u32_e32 v171, s47, v97
	ds_read_b128 v[130:133], v154
	ds_read_b128 v[134:137], v154 offset:1024
	ds_read_b128 v[150:153], v154 offset:2048
	ds_read_b128 v[154:157], v154 offset:3072
	ds_read_b128 v[158:161], v171
	ds_read_b128 v[162:165], v171 offset:1024
	ds_read_b128 v[166:169], v171 offset:2048
	ds_read_b128 v[172:175], v171 offset:3072
	v_lshl_add_u64 v[208:209], s[44:45], 0, v[146:147]
	s_add_i32 m0, s13, 0xc000
	ds_read_b128 v[176:179], v170
	ds_read_b128 v[180:183], v170 offset:1024
	ds_read_b128 v[184:187], v170 offset:2048
	ds_read_b128 v[188:191], v170 offset:3072
	ds_read_b128 v[192:195], v170 offset:4096
	ds_read_b128 v[196:199], v170 offset:5120
	ds_read_b128 v[200:203], v170 offset:6144
	ds_read_b128 v[204:207], v170 offset:7168
	global_load_lds_dwordx4 v[208:209], off
	v_lshl_add_u64 v[208:209], s[44:45], 0, v[148:149]
	s_add_i32 m0, s13, 0xe000
	s_nop 0
	global_load_lds_dwordx4 v[208:209], off
	s_waitcnt vmcnt(8)
	s_waitcnt lgkmcnt(0)
	s_barrier
	s_waitcnt lgkmcnt(0)
	v_mfma_f32_16x16x32_bf16 v[122:125], v[130:133], v[176:179], v[122:125]
	v_mfma_f32_16x16x32_bf16 v[126:129], v[150:153], v[176:179], v[126:129]
	v_mfma_f32_16x16x32_bf16 v[110:113], v[130:133], v[184:187], v[110:113]
	v_mfma_f32_16x16x32_bf16 v[106:109], v[150:153], v[184:187], v[106:109]
	v_mfma_f32_16x16x32_bf16 v[92:95], v[130:133], v[192:195], v[92:95]
	v_mfma_f32_16x16x32_bf16 v[88:91], v[150:153], v[192:195], v[88:91]
	v_mfma_f32_16x16x32_bf16 v[76:79], v[130:133], v[200:203], v[76:79]
	v_mfma_f32_16x16x32_bf16 v[72:75], v[150:153], v[200:203], v[72:75]
	v_mfma_f32_16x16x32_bf16 v[122:125], v[134:137], v[180:183], v[122:125]
	v_mfma_f32_16x16x32_bf16 v[126:129], v[154:157], v[180:183], v[126:129]
	v_mfma_f32_16x16x32_bf16 v[110:113], v[134:137], v[188:191], v[110:113]
	v_mfma_f32_16x16x32_bf16 v[106:109], v[154:157], v[188:191], v[106:109]
	v_mfma_f32_16x16x32_bf16 v[92:95], v[134:137], v[196:199], v[92:95]
	v_mfma_f32_16x16x32_bf16 v[88:91], v[154:157], v[196:199], v[88:91]
	v_mfma_f32_16x16x32_bf16 v[76:79], v[134:137], v[204:207], v[76:79]
	v_mfma_f32_16x16x32_bf16 v[72:75], v[154:157], v[204:207], v[72:75]
	v_mfma_f32_16x16x32_bf16 v[118:121], v[158:161], v[176:179], v[118:121]
	v_mfma_f32_16x16x32_bf16 v[114:117], v[166:169], v[176:179], v[114:117]
	v_mfma_f32_16x16x32_bf16 v[102:105], v[158:161], v[184:187], v[102:105]
	v_mfma_f32_16x16x32_bf16 v[98:101], v[166:169], v[184:187], v[98:101]
	v_mfma_f32_16x16x32_bf16 v[84:87], v[158:161], v[192:195], v[84:87]
	v_mfma_f32_16x16x32_bf16 v[80:83], v[166:169], v[192:195], v[80:83]
	v_mfma_f32_16x16x32_bf16 v[68:71], v[158:161], v[200:203], v[68:71]
	v_mfma_f32_16x16x32_bf16 v[64:67], v[166:169], v[200:203], v[64:67]
	v_mfma_f32_16x16x32_bf16 v[118:121], v[162:165], v[180:183], v[118:121]
	v_mfma_f32_16x16x32_bf16 v[114:117], v[172:175], v[180:183], v[114:117]
	v_mfma_f32_16x16x32_bf16 v[102:105], v[162:165], v[188:191], v[102:105]
	v_mfma_f32_16x16x32_bf16 v[98:101], v[172:175], v[188:191], v[98:101]
	v_mfma_f32_16x16x32_bf16 v[84:87], v[162:165], v[196:199], v[84:87]
	v_mfma_f32_16x16x32_bf16 v[80:83], v[172:175], v[196:199], v[80:83]
	v_mfma_f32_16x16x32_bf16 v[68:71], v[162:165], v[204:207], v[68:71]
	v_mfma_f32_16x16x32_bf16 v[64:67], v[172:175], v[204:207], v[64:67]
	s_barrier
	s_add_i32 s46, s46, s12
	v_lshl_add_u64 v[208:209], s[38:39], 0, v[140:141]
	s_mov_b32 m0, s46
	ds_read_b128 v[176:179], v170 offset:16384
	ds_read_b128 v[180:183], v170 offset:17408
	ds_read_b128 v[184:187], v170 offset:18432
	ds_read_b128 v[188:191], v170 offset:19456
	ds_read_b128 v[192:195], v170 offset:20480
	ds_read_b128 v[196:199], v170 offset:21504
	ds_read_b128 v[200:203], v170 offset:22528
	ds_read_b128 v[204:207], v170 offset:23552
	global_load_lds_dwordx4 v[208:209], off
	s_add_i32 m0, s46, 0x2000
	v_lshl_add_u64 v[218:219], s[38:39], 0, v[144:145]
	s_add_u32 s38, s38, s62
	s_addc_u32 s39, s39, s63
	s_add_i32 s46, s47, s12
	global_load_lds_dwordx4 v[218:219], off
	v_lshl_add_u64 v[220:221], s[38:39], 0, v[140:141]
	s_mov_b32 m0, s46
	v_lshl_add_u64 v[222:223], s[38:39], 0, v[144:145]
	global_load_lds_dwordx4 v[220:221], off
	s_add_i32 m0, s46, 0x2000
	v_lshl_add_u64 v[224:225], s[6:7], 0, v[138:139]
	global_load_lds_dwordx4 v[222:223], off
	s_mov_b32 m0, s13
	v_lshl_add_u64 v[226:227], s[6:7], 0, v[142:143]
	global_load_lds_dwordx4 v[224:225], off
	s_mov_b32 m0, s40
	s_nop 0
	global_load_lds_dwordx4 v[226:227], off
	s_waitcnt vmcnt(8)
	s_waitcnt lgkmcnt(0)
	s_barrier
; #define PG8_STAGE(bufoff, gbase, voff) do { _Pragma("unroll") for (int _i = 0; _i < 2; ++_i) \
;         __builtin_amdgcn_global_load_lds((const unsigned*)((const char*)(gbase) + (voff)[_i]), (PG8_LAS unsigned*)(lds + (bufoff) + ldsw + _i * 8192), 16, 0, 0); } while (0)
; #define PG8_LDA(dst, b, h) do { _Pragma("unroll") for (int m = 0; m < 4; ++m) _Pragma("unroll") for (int k = 0; k < 2; ++k) dst[m][k] = *(const PG8_LAS bf16x8*)(lds + PG8_SA(b, h) + aoff + m * 2048 + k * 1024); } while (0)
; #define PG8_LDB(dst, b, h) do { _Pragma("unroll") for (int n = 0; n < 2; ++n) _Pragma("unroll") for (int k = 0; k < 2; ++k) dst[n][k] = *(const PG8_LAS bf16x8*)(lds + PG8_SB(b, h) + boff + n * 2048 + k * 1024); } while (0)
; #define PG8_MMA(ai, bj, At, Bt) do { __builtin_amdgcn_s_setprio(1); _Pragma("unroll") for (int m = 0; m < 4; ++m) _Pragma("unroll") for (int n = 0; n < 2; ++n) _Pragma("unroll") for (int k = 0; k < 2; ++k) \
;         acc[ai][bj][m][n] = __builtin_amdgcn_mfma_f32_16x16x32_bf16(Bt[n][k], At[m][k], acc[ai][bj][m][n], 0, 0, 0); __builtin_amdgcn_s_setprio(0); } while (0)
; #define PG8_WAIT_V(n) asm volatile("s_waitcnt vmcnt(" #n ")" ::: "memory")
; #define PG8_WAIT_L(n) asm volatile("s_waitcnt lgkmcnt(" #n ")" ::: "memory")
; #define PG8_BAR __builtin_amdgcn_s_barrier()
; #define PG8_SCHED __builtin_amdgcn_sched_barrier(0)
; template <class Epi>
; __device__ __forceinline__ void gemm_phase(PG8_LAS unsigned char* lds, const Gemm g, const StaticOrder& S, const Epi& E, const int wave_s) {
;     ...
;             PG8_WAIT_V(8); PG8_WAIT_L(0); PG8_BAR; PG8_MMA(1, 0, At, B0); PG8_MMA(1, 1, At, B1); PG8_BAR; PG8_SCHED;
;             PG8_LDB(B0, 1, 0); PG8_LDB(B1, 1, 1); PG8_SCHED; PG8_LDA(At, 1, 0); PG8_STAGE(PG8_SA(0, 1), a2 + hstepA, voffA);
;             PG8_WAIT_V(8); PG8_WAIT_L(0); PG8_BAR; PG8_MMA(0, 0, At, B0); PG8_MMA(0, 1, At, B1); PG8_BAR; PG8_SCHED;
	s_waitcnt lgkmcnt(0)
	v_mfma_f32_16x16x32_bf16 v[60:63], v[130:133], v[176:179], v[60:63]
	v_mfma_f32_16x16x32_bf16 v[56:59], v[150:153], v[176:179], v[56:59]
	v_mfma_f32_16x16x32_bf16 v[44:47], v[130:133], v[184:187], v[44:47]
	v_mfma_f32_16x16x32_bf16 v[40:43], v[150:153], v[184:187], v[40:43]
	v_mfma_f32_16x16x32_bf16 v[28:31], v[130:133], v[192:195], v[28:31]
	v_mfma_f32_16x16x32_bf16 v[24:27], v[150:153], v[192:195], v[24:27]
	v_mfma_f32_16x16x32_bf16 v[12:15], v[130:133], v[200:203], v[12:15]
	v_mfma_f32_16x16x32_bf16 v[8:11], v[150:153], v[200:203], v[8:11]
	v_mfma_f32_16x16x32_bf16 v[60:63], v[134:137], v[180:183], v[60:63]
	v_mfma_f32_16x16x32_bf16 v[56:59], v[154:157], v[180:183], v[56:59]
	v_mfma_f32_16x16x32_bf16 v[44:47], v[134:137], v[188:191], v[44:47]
	v_mfma_f32_16x16x32_bf16 v[40:43], v[154:157], v[188:191], v[40:43]
	v_mfma_f32_16x16x32_bf16 v[28:31], v[134:137], v[196:199], v[28:31]
	v_mfma_f32_16x16x32_bf16 v[24:27], v[154:157], v[196:199], v[24:27]
	v_mfma_f32_16x16x32_bf16 v[12:15], v[134:137], v[204:207], v[12:15]
	v_mfma_f32_16x16x32_bf16 v[8:11], v[154:157], v[204:207], v[8:11]
	v_mfma_f32_16x16x32_bf16 v[52:55], v[158:161], v[176:179], v[52:55]
	v_mfma_f32_16x16x32_bf16 v[48:51], v[166:169], v[176:179], v[48:51]
	v_mfma_f32_16x16x32_bf16 v[36:39], v[158:161], v[184:187], v[36:39]
	v_mfma_f32_16x16x32_bf16 v[32:35], v[166:169], v[184:187], v[32:35]
	v_mfma_f32_16x16x32_bf16 v[20:23], v[158:161], v[192:195], v[20:23]
	v_mfma_f32_16x16x32_bf16 v[16:19], v[166:169], v[192:195], v[16:19]
	v_mfma_f32_16x16x32_bf16 v[4:7], v[158:161], v[200:203], v[4:7]
	v_mfma_f32_16x16x32_bf16 v[0:3], v[166:169], v[200:203], v[0:3]
	v_mfma_f32_16x16x32_bf16 v[52:55], v[162:165], v[180:183], v[52:55]
	v_mfma_f32_16x16x32_bf16 v[48:51], v[172:175], v[180:183], v[48:51]
	v_mfma_f32_16x16x32_bf16 v[36:39], v[162:165], v[188:191], v[36:39]
	v_mfma_f32_16x16x32_bf16 v[32:35], v[172:175], v[188:191], v[32:35]
	v_mfma_f32_16x16x32_bf16 v[20:23], v[162:165], v[196:199], v[20:23]
	v_mfma_f32_16x16x32_bf16 v[16:19], v[172:175], v[196:199], v[16:19]
	v_mfma_f32_16x16x32_bf16 v[4:7], v[162:165], v[204:207], v[4:7]
	v_mfma_f32_16x16x32_bf16 v[0:3], v[172:175], v[204:207], v[0:3]
	s_barrier
	s_add_i32 s38, 0, 0x18000
	s_add_i32 s39, 0, 0x1c000
	v_add_u32_e32 v154, s38, v97
	v_add_u32_e32 v171, s39, v97
	ds_read_b128 v[130:133], v154
	ds_read_b128 v[134:137], v154 offset:1024
	ds_read_b128 v[150:153], v154 offset:2048
	ds_read_b128 v[154:157], v154 offset:3072
	ds_read_b128 v[158:161], v171
	ds_read_b128 v[162:165], v171 offset:1024
	ds_read_b128 v[166:169], v171 offset:2048
	ds_read_b128 v[172:175], v171 offset:3072
	s_add_u32 s6, s6, s60
	s_addc_u32 s7, s7, s61
	s_mov_b32 m0, s41
	v_lshl_add_u64 v[228:229], s[6:7], 0, v[138:139]
	ds_read_b128 v[176:179], v170 offset:32768
	ds_read_b128 v[180:183], v170 offset:33792
	ds_read_b128 v[184:187], v170 offset:34816
	ds_read_b128 v[188:191], v170 offset:35840
	ds_read_b128 v[192:195], v170 offset:36864
	ds_read_b128 v[196:199], v170 offset:37888
	ds_read_b128 v[200:203], v170 offset:38912
	ds_read_b128 v[204:207], v170 offset:39936
	global_load_lds_dwordx4 v[228:229], off
	v_lshl_add_u64 v[228:229], s[6:7], 0, v[142:143]
	s_mov_b32 m0, s4
	s_nop 0
	global_load_lds_dwordx4 v[228:229], off
	s_waitcnt vmcnt(8)
	s_waitcnt lgkmcnt(0)
	s_barrier
	s_waitcnt lgkmcnt(0)
	v_mfma_f32_16x16x32_bf16 v[122:125], v[130:133], v[176:179], v[122:125]
	v_mfma_f32_16x16x32_bf16 v[126:129], v[150:153], v[176:179], v[126:129]
	v_mfma_f32_16x16x32_bf16 v[110:113], v[130:133], v[184:187], v[110:113]
	v_mfma_f32_16x16x32_bf16 v[106:109], v[150:153], v[184:187], v[106:109]
	v_mfma_f32_16x16x32_bf16 v[92:95], v[130:133], v[192:195], v[92:95]
	v_mfma_f32_16x16x32_bf16 v[88:91], v[150:153], v[192:195], v[88:91]
	v_mfma_f32_16x16x32_bf16 v[76:79], v[130:133], v[200:203], v[76:79]
	v_mfma_f32_16x16x32_bf16 v[72:75], v[150:153], v[200:203], v[72:75]
	v_mfma_f32_16x16x32_bf16 v[122:125], v[134:137], v[180:183], v[122:125]
	v_mfma_f32_16x16x32_bf16 v[126:129], v[154:157], v[180:183], v[126:129]
	v_mfma_f32_16x16x32_bf16 v[110:113], v[134:137], v[188:191], v[110:113]
	v_mfma_f32_16x16x32_bf16 v[106:109], v[154:157], v[188:191], v[106:109]
	v_mfma_f32_16x16x32_bf16 v[92:95], v[134:137], v[196:199], v[92:95]
	v_mfma_f32_16x16x32_bf16 v[88:91], v[154:157], v[196:199], v[88:91]
	v_mfma_f32_16x16x32_bf16 v[76:79], v[134:137], v[204:207], v[76:79]
	v_mfma_f32_16x16x32_bf16 v[72:75], v[154:157], v[204:207], v[72:75]
	v_mfma_f32_16x16x32_bf16 v[118:121], v[158:161], v[176:179], v[118:121]
	v_mfma_f32_16x16x32_bf16 v[114:117], v[166:169], v[176:179], v[114:117]
	v_mfma_f32_16x16x32_bf16 v[102:105], v[158:161], v[184:187], v[102:105]
	v_mfma_f32_16x16x32_bf16 v[98:101], v[166:169], v[184:187], v[98:101]
	v_mfma_f32_16x16x32_bf16 v[84:87], v[158:161], v[192:195], v[84:87]
	v_mfma_f32_16x16x32_bf16 v[80:83], v[166:169], v[192:195], v[80:83]
	v_mfma_f32_16x16x32_bf16 v[68:71], v[158:161], v[200:203], v[68:71]
	v_mfma_f32_16x16x32_bf16 v[64:67], v[166:169], v[200:203], v[64:67]
	v_mfma_f32_16x16x32_bf16 v[118:121], v[162:165], v[180:183], v[118:121]
	v_mfma_f32_16x16x32_bf16 v[114:117], v[172:175], v[180:183], v[114:117]
	v_mfma_f32_16x16x32_bf16 v[102:105], v[162:165], v[188:191], v[102:105]
	v_mfma_f32_16x16x32_bf16 v[98:101], v[172:175], v[188:191], v[98:101]
	v_mfma_f32_16x16x32_bf16 v[84:87], v[162:165], v[196:199], v[84:87]
	v_mfma_f32_16x16x32_bf16 v[80:83], v[172:175], v[196:199], v[80:83]
	v_mfma_f32_16x16x32_bf16 v[68:71], v[162:165], v[204:207], v[68:71]
	v_mfma_f32_16x16x32_bf16 v[64:67], v[172:175], v[204:207], v[64:67]
	s_barrier
; #define PG8_STAGE(bufoff, gbase, voff) do { _Pragma("unroll") for (int _i = 0; _i < 2; ++_i) \
;         __builtin_amdgcn_global_load_lds((const unsigned*)((const char*)(gbase) + (voff)[_i]), (PG8_LAS unsigned*)(lds + (bufoff) + ldsw + _i * 8192), 16, 0, 0); } while (0)
; #define PG8_LDA(dst, b, h) do { _Pragma("unroll") for (int m = 0; m < 4; ++m) _Pragma("unroll") for (int k = 0; k < 2; ++k) dst[m][k] = *(const PG8_LAS bf16x8*)(lds + PG8_SA(b, h) + aoff + m * 2048 + k * 1024); } while (0)
; #define PG8_MMA(ai, bj, At, Bt) do { __builtin_amdgcn_s_setprio(1); _Pragma("unroll") for (int m = 0; m < 4; ++m) _Pragma("unroll") for (int n = 0; n < 2; ++n) _Pragma("unroll") for (int k = 0; k < 2; ++k) \
;         acc[ai][bj][m][n] = __builtin_amdgcn_mfma_f32_16x16x32_bf16(Bt[n][k], At[m][k], acc[ai][bj][m][n], 0, 0, 0); __builtin_amdgcn_s_setprio(0); } while (0)
; #define PG8_WAIT_V(n) asm volatile("s_waitcnt vmcnt(" #n ")" ::: "memory")
; #define PG8_WAIT_L(n) asm volatile("s_waitcnt lgkmcnt(" #n ")" ::: "memory")
; #define PG8_BAR __builtin_amdgcn_s_barrier()
; #define PG8_SCHED __builtin_amdgcn_sched_barrier(0)
; template <class Epi>
; __device__ __forceinline__ void gemm_phase(PG8_LAS unsigned char* lds, const Gemm g, const StaticOrder& S, const Epi& E, const int wave_s) {
;     ...
;             PG8_LDA(At, 1, 1); PG8_STAGE(PG8_SB(1, 0), b3, voffB); PG8_STAGE(PG8_SB(1, 1), b3 + hstepB, voffB); PG8_STAGE(PG8_SA(1, 0), a3, voffA);
;             PG8_WAIT_V(8); PG8_WAIT_L(0); PG8_BAR; PG8_MMA(1, 0, At, B0); PG8_MMA(1, 1, At, B1); PG8_BAR; PG8_SCHED;
;         }
	s_add_i32 s6, s38, s12
	v_lshl_add_u64 v[208:209], v[208:209], 0, s[52:53]
	s_mov_b32 m0, s6
	ds_read_b128 v[176:179], v170 offset:49152
	ds_read_b128 v[180:183], v170 offset:50176
	ds_read_b128 v[184:187], v170 offset:51200
	ds_read_b128 v[188:191], v170 offset:52224
	ds_read_b128 v[192:195], v170 offset:53248
	ds_read_b128 v[196:199], v170 offset:54272
	ds_read_b128 v[200:203], v170 offset:55296
	ds_read_b128 v[204:207], v170 offset:56320
	global_load_lds_dwordx4 v[208:209], off
	v_lshl_add_u64 v[208:209], v[218:219], 0, s[52:53]
	s_add_i32 m0, s6, 0x2000
	s_add_i32 s6, s39, s12
	global_load_lds_dwordx4 v[208:209], off
	v_lshl_add_u64 v[208:209], v[220:221], 0, s[52:53]
	s_mov_b32 m0, s6
	s_nop 0
	global_load_lds_dwordx4 v[208:209], off
	v_lshl_add_u64 v[208:209], v[222:223], 0, s[52:53]
	s_add_i32 m0, s6, 0x2000
	s_nop 0
	global_load_lds_dwordx4 v[208:209], off
	v_lshl_add_u64 v[208:209], v[224:225], 0, s[52:53]
	s_mov_b32 m0, s10
	s_nop 0
	global_load_lds_dwordx4 v[208:209], off
	v_lshl_add_u64 v[208:209], v[226:227], 0, s[52:53]
	s_mov_b32 m0, s11
	s_nop 0
	global_load_lds_dwordx4 v[208:209], off
	s_waitcnt vmcnt(8)
	s_waitcnt lgkmcnt(0)
	s_barrier
	s_waitcnt lgkmcnt(0)
	v_mfma_f32_16x16x32_bf16 v[60:63], v[130:133], v[176:179], v[60:63]
	v_mfma_f32_16x16x32_bf16 v[56:59], v[150:153], v[176:179], v[56:59]
	s_add_u32 s44, s44, 0x100
	s_addc_u32 s45, s45, 0
	s_add_u32 s9, s9, 0x100
	s_addc_u32 s25, s25, 0
	s_mov_b32 s6, s36
	s_cmp_ge_i32 s36, s68
	v_mfma_f32_16x16x32_bf16 v[44:47], v[130:133], v[184:187], v[44:47]
	v_mfma_f32_16x16x32_bf16 v[40:43], v[150:153], v[184:187], v[40:43]
	v_mfma_f32_16x16x32_bf16 v[28:31], v[130:133], v[192:195], v[28:31]
	v_mfma_f32_16x16x32_bf16 v[24:27], v[150:153], v[192:195], v[24:27]
	v_mfma_f32_16x16x32_bf16 v[12:15], v[130:133], v[200:203], v[12:15]
	v_mfma_f32_16x16x32_bf16 v[8:11], v[150:153], v[200:203], v[8:11]
	v_mfma_f32_16x16x32_bf16 v[60:63], v[134:137], v[180:183], v[60:63]
	v_mfma_f32_16x16x32_bf16 v[56:59], v[154:157], v[180:183], v[56:59]
	v_mfma_f32_16x16x32_bf16 v[44:47], v[134:137], v[188:191], v[44:47]
	v_mfma_f32_16x16x32_bf16 v[40:43], v[154:157], v[188:191], v[40:43]
	v_mfma_f32_16x16x32_bf16 v[28:31], v[134:137], v[196:199], v[28:31]
	v_mfma_f32_16x16x32_bf16 v[24:27], v[154:157], v[196:199], v[24:27]
	v_mfma_f32_16x16x32_bf16 v[12:15], v[134:137], v[204:207], v[12:15]
	v_mfma_f32_16x16x32_bf16 v[8:11], v[154:157], v[204:207], v[8:11]
	v_mfma_f32_16x16x32_bf16 v[52:55], v[158:161], v[176:179], v[52:55]
	v_mfma_f32_16x16x32_bf16 v[48:51], v[166:169], v[176:179], v[48:51]
	v_mfma_f32_16x16x32_bf16 v[36:39], v[158:161], v[184:187], v[36:39]
	v_mfma_f32_16x16x32_bf16 v[32:35], v[166:169], v[184:187], v[32:35]
	v_mfma_f32_16x16x32_bf16 v[20:23], v[158:161], v[192:195], v[20:23]
	v_mfma_f32_16x16x32_bf16 v[16:19], v[166:169], v[192:195], v[16:19]
	v_mfma_f32_16x16x32_bf16 v[4:7], v[158:161], v[200:203], v[4:7]
	v_mfma_f32_16x16x32_bf16 v[0:3], v[166:169], v[200:203], v[0:3]
	v_mfma_f32_16x16x32_bf16 v[52:55], v[162:165], v[180:183], v[52:55]
	v_mfma_f32_16x16x32_bf16 v[48:51], v[172:175], v[180:183], v[48:51]
	v_mfma_f32_16x16x32_bf16 v[36:39], v[162:165], v[188:191], v[36:39]
	v_mfma_f32_16x16x32_bf16 v[32:35], v[172:175], v[188:191], v[32:35]
	v_mfma_f32_16x16x32_bf16 v[20:23], v[162:165], v[196:199], v[20:23]
	v_mfma_f32_16x16x32_bf16 v[16:19], v[172:175], v[196:199], v[16:19]
	v_mfma_f32_16x16x32_bf16 v[4:7], v[162:165], v[204:207], v[4:7]
	v_mfma_f32_16x16x32_bf16 v[0:3], v[172:175], v[204:207], v[0:3]
	s_barrier
	s_cbranch_scc0 .LBB0_336
	s_setprio 0

; #define PG8_STAGE(bufoff, gbase, voff) do { _Pragma("unroll") for (int _i = 0; _i < 2; ++_i) \
;         __builtin_amdgcn_global_load_lds((const unsigned*)((const char*)(gbase) + (voff)[_i]), (PG8_LAS unsigned*)(lds + (bufoff) + ldsw + _i * 8192), 16, 0, 0); } while (0)
; #define PG8_LDA(dst, b, h) do { _Pragma("unroll") for (int m = 0; m < 4; ++m) _Pragma("unroll") for (int k = 0; k < 2; ++k) dst[m][k] = *(const PG8_LAS bf16x8*)(lds + PG8_SA(b, h) + aoff + m * 2048 + k * 1024); } while (0)
; #define PG8_LDB(dst, b, h) do { _Pragma("unroll") for (int n = 0; n < 2; ++n) _Pragma("unroll") for (int k = 0; k < 2; ++k) dst[n][k] = *(const PG8_LAS bf16x8*)(lds + PG8_SB(b, h) + boff + n * 2048 + k * 1024); } while (0)
; #define PG8_MMA(ai, bj, At, Bt) do { __builtin_amdgcn_s_setprio(1); _Pragma("unroll") for (int m = 0; m < 4; ++m) _Pragma("unroll") for (int n = 0; n < 2; ++n) _Pragma("unroll") for (int k = 0; k < 2; ++k) \
;         acc[ai][bj][m][n] = __builtin_amdgcn_mfma_f32_16x16x32_bf16(Bt[n][k], At[m][k], acc[ai][bj][m][n], 0, 0, 0); __builtin_amdgcn_s_setprio(0); } while (0)
; #define PG8_WAIT_V(n) asm volatile("s_waitcnt vmcnt(" #n ")" ::: "memory")
; #define PG8_WAIT_L(n) asm volatile("s_waitcnt lgkmcnt(" #n ")" ::: "memory")
; #define PG8_BAR __builtin_amdgcn_s_barrier()
; #define PG8_SCHED __builtin_amdgcn_sched_barrier(0)
; template <class Epi>
; __device__ __forceinline__ void gemm_phase(PG8_LAS unsigned char* lds, const Gemm g, const StaticOrder& S, const Epi& E, const int wave_s) {
;     ...
;         for (int t = 0; t < nt; t += 2) {
;             const bool last = (t == nt - 2);
;             const char* a1 = cA + (size_t)(t + 1) * kstep;
;             const char* a2 = last ? nA : cA + (size_t)(t + 2) * kstep; const char* b2 = last ? nB : cB + (size_t)(t + 2) * kstep;
;             const char* a3 = a2 + kstep; const char* b3 = b2 + kstep;
;             PG8_LDB(B0, 0, 0); PG8_LDB(B1, 0, 1); PG8_SCHED; PG8_LDA(At, 0, 0); PG8_STAGE(PG8_SA(1, 1), a1 + hstepA, voffA);
;             PG8_WAIT_V(8); PG8_WAIT_L(0); PG8_BAR; PG8_MMA(0, 0, At, B0); PG8_MMA(0, 1, At, B1); PG8_BAR; PG8_SCHED;
;             PG8_LDA(At, 0, 1); PG8_STAGE(PG8_SB(0, 0), b2, voffB); PG8_STAGE(PG8_SB(0, 1), b2 + hstepB, voffB); PG8_STAGE(PG8_SA(0, 0), a2, voffA);
;             PG8_WAIT_V(8); PG8_WAIT_L(0); PG8_BAR; PG8_MMA(1, 0, At, B0); PG8_MMA(1, 1, At, B1); PG8_BAR; PG8_SCHED;
.Lg2_prio_done:
.LBB0_459:
	s_add_i32 s12, s6, 2
	s_add_u32 s13, s44, 0x80
	s_addc_u32 s7, s45, 0
	s_add_i32 s16, 0, 0x10000
	s_cmp_eq_u32 s36, s6
	s_cselect_b32 s7, s71, s7
	s_cselect_b32 s6, s70, s13
	v_add_u32_e32 v154, s16, v97
	s_cselect_b32 s39, s87, s9
	s_cselect_b32 s38, s86, s8
	s_add_i32 s13, 0, 0x14000
	ds_read_b128 v[130:133], v154
	ds_read_b128 v[146:149], v154 offset:1024
	ds_read_b128 v[150:153], v154 offset:2048
	ds_read_b128 v[158:161], v154 offset:3072
	v_add_u32_e32 v154, s13, v97
	ds_read_b128 v[162:165], v154
	ds_read_b128 v[166:169], v154 offset:1024
	ds_read_b128 v[170:173], v154 offset:2048
	ds_read_b128 v[174:177], v154 offset:3072
	v_lshl_add_u64 v[154:155], s[44:45], 0, v[142:143]
	s_add_i32 m0, s40, 0xc000
	ds_read_b128 v[178:181], v156
	ds_read_b128 v[182:185], v156 offset:1024
	ds_read_b128 v[186:189], v156 offset:2048
	ds_read_b128 v[190:193], v156 offset:3072
	ds_read_b128 v[194:197], v156 offset:4096
	ds_read_b128 v[198:201], v156 offset:5120
	ds_read_b128 v[202:205], v156 offset:6144
	ds_read_b128 v[206:209], v156 offset:7168
	global_load_lds_dwordx4 v[154:155], off
	v_lshl_add_u64 v[154:155], s[44:45], 0, v[144:145]
	s_add_i32 m0, s40, 0xe000
	s_nop 0
	global_load_lds_dwordx4 v[154:155], off
	s_waitcnt vmcnt(8)
	s_waitcnt lgkmcnt(0)
	s_barrier
	s_waitcnt lgkmcnt(0)
	v_mfma_f32_16x16x32_bf16 v[126:129], v[130:133], v[178:181], v[126:129]
	v_mfma_f32_16x16x32_bf16 v[122:125], v[150:153], v[178:181], v[122:125]
	v_mfma_f32_16x16x32_bf16 v[110:113], v[130:133], v[186:189], v[110:113]
	v_mfma_f32_16x16x32_bf16 v[106:109], v[150:153], v[186:189], v[106:109]
	v_mfma_f32_16x16x32_bf16 v[92:95], v[130:133], v[194:197], v[92:95]
	v_mfma_f32_16x16x32_bf16 v[88:91], v[150:153], v[194:197], v[88:91]
	v_mfma_f32_16x16x32_bf16 v[76:79], v[130:133], v[202:205], v[76:79]
	v_mfma_f32_16x16x32_bf16 v[72:75], v[150:153], v[202:205], v[72:75]
	v_mfma_f32_16x16x32_bf16 v[126:129], v[146:149], v[182:185], v[126:129]
	v_mfma_f32_16x16x32_bf16 v[122:125], v[158:161], v[182:185], v[122:125]
	v_mfma_f32_16x16x32_bf16 v[110:113], v[146:149], v[190:193], v[110:113]
	v_mfma_f32_16x16x32_bf16 v[106:109], v[158:161], v[190:193], v[106:109]
	v_mfma_f32_16x16x32_bf16 v[92:95], v[146:149], v[198:201], v[92:95]
	v_mfma_f32_16x16x32_bf16 v[88:91], v[158:161], v[198:201], v[88:91]
	v_mfma_f32_16x16x32_bf16 v[76:79], v[146:149], v[206:209], v[76:79]
	v_mfma_f32_16x16x32_bf16 v[72:75], v[158:161], v[206:209], v[72:75]
	v_mfma_f32_16x16x32_bf16 v[118:121], v[162:165], v[178:181], v[118:121]
	v_mfma_f32_16x16x32_bf16 v[114:117], v[170:173], v[178:181], v[114:117]
	v_mfma_f32_16x16x32_bf16 v[102:105], v[162:165], v[186:189], v[102:105]
	v_mfma_f32_16x16x32_bf16 v[98:101], v[170:173], v[186:189], v[98:101]
	v_mfma_f32_16x16x32_bf16 v[84:87], v[162:165], v[194:197], v[84:87]
	v_mfma_f32_16x16x32_bf16 v[80:83], v[170:173], v[194:197], v[80:83]
	v_mfma_f32_16x16x32_bf16 v[68:71], v[162:165], v[202:205], v[68:71]
	v_mfma_f32_16x16x32_bf16 v[64:67], v[170:173], v[202:205], v[64:67]
	v_mfma_f32_16x16x32_bf16 v[118:121], v[166:169], v[182:185], v[118:121]
	v_mfma_f32_16x16x32_bf16 v[114:117], v[174:177], v[182:185], v[114:117]
	v_mfma_f32_16x16x32_bf16 v[102:105], v[166:169], v[190:193], v[102:105]
	v_mfma_f32_16x16x32_bf16 v[98:101], v[174:177], v[190:193], v[98:101]
	v_mfma_f32_16x16x32_bf16 v[84:87], v[166:169], v[198:201], v[84:87]
	v_mfma_f32_16x16x32_bf16 v[80:83], v[174:177], v[198:201], v[80:83]
	v_mfma_f32_16x16x32_bf16 v[68:71], v[166:169], v[206:209], v[68:71]
	v_mfma_f32_16x16x32_bf16 v[64:67], v[174:177], v[206:209], v[64:67]
	s_barrier
	s_add_i32 s16, s16, s37
	v_lshl_add_u64 v[154:155], s[38:39], 0, v[136:137]
	s_mov_b32 m0, s16
	ds_read_b128 v[178:181], v156 offset:16384
	ds_read_b128 v[182:185], v156 offset:17408
	ds_read_b128 v[186:189], v156 offset:18432
	ds_read_b128 v[190:193], v156 offset:19456
	ds_read_b128 v[194:197], v156 offset:20480
	ds_read_b128 v[198:201], v156 offset:21504
	ds_read_b128 v[202:205], v156 offset:22528
	ds_read_b128 v[206:209], v156 offset:23552
	global_load_lds_dwordx4 v[154:155], off
	s_add_i32 m0, s16, 0x2000
	v_lshl_add_u64 v[218:219], s[38:39], 0, v[140:141]
	s_add_u32 s38, s38, s50
	s_addc_u32 s39, s39, s51
	s_add_i32 s13, s13, s37
	global_load_lds_dwordx4 v[218:219], off
	v_lshl_add_u64 v[220:221], s[38:39], 0, v[136:137]
	s_mov_b32 m0, s13
	v_lshl_add_u64 v[222:223], s[38:39], 0, v[140:141]
	global_load_lds_dwordx4 v[220:221], off
	s_add_i32 m0, s13, 0x2000
	v_lshl_add_u64 v[224:225], s[6:7], 0, v[134:135]
	global_load_lds_dwordx4 v[222:223], off
	s_mov_b32 m0, s40
	v_lshl_add_u64 v[226:227], s[6:7], 0, v[138:139]
	global_load_lds_dwordx4 v[224:225], off
	s_mov_b32 m0, s41
	s_nop 0
	global_load_lds_dwordx4 v[226:227], off
	s_waitcnt vmcnt(8)
	s_waitcnt lgkmcnt(0)
	s_barrier
; #define PG8_STAGE(bufoff, gbase, voff) do { _Pragma("unroll") for (int _i = 0; _i < 2; ++_i) \
;         __builtin_amdgcn_global_load_lds((const unsigned*)((const char*)(gbase) + (voff)[_i]), (PG8_LAS unsigned*)(lds + (bufoff) + ldsw + _i * 8192), 16, 0, 0); } while (0)
; #define PG8_LDA(dst, b, h) do { _Pragma("unroll") for (int m = 0; m < 4; ++m) _Pragma("unroll") for (int k = 0; k < 2; ++k) dst[m][k] = *(const PG8_LAS bf16x8*)(lds + PG8_SA(b, h) + aoff + m * 2048 + k * 1024); } while (0)
; #define PG8_LDB(dst, b, h) do { _Pragma("unroll") for (int n = 0; n < 2; ++n) _Pragma("unroll") for (int k = 0; k < 2; ++k) dst[n][k] = *(const PG8_LAS bf16x8*)(lds + PG8_SB(b, h) + boff + n * 2048 + k * 1024); } while (0)
; #define PG8_MMA(ai, bj, At, Bt) do { __builtin_amdgcn_s_setprio(1); _Pragma("unroll") for (int m = 0; m < 4; ++m) _Pragma("unroll") for (int n = 0; n < 2; ++n) _Pragma("unroll") for (int k = 0; k < 2; ++k) \
;         acc[ai][bj][m][n] = __builtin_amdgcn_mfma_f32_16x16x32_bf16(Bt[n][k], At[m][k], acc[ai][bj][m][n], 0, 0, 0); __builtin_amdgcn_s_setprio(0); } while (0)
; #define PG8_WAIT_V(n) asm volatile("s_waitcnt vmcnt(" #n ")" ::: "memory")
; #define PG8_WAIT_L(n) asm volatile("s_waitcnt lgkmcnt(" #n ")" ::: "memory")
; #define PG8_BAR __builtin_amdgcn_s_barrier()
; #define PG8_SCHED __builtin_amdgcn_sched_barrier(0)
; template <class Epi>
; __device__ __forceinline__ void gemm_phase(PG8_LAS unsigned char* lds, const Gemm g, const StaticOrder& S, const Epi& E, const int wave_s) {
;     ...
;             PG8_WAIT_V(8); PG8_WAIT_L(0); PG8_BAR; PG8_MMA(1, 0, At, B0); PG8_MMA(1, 1, At, B1); PG8_BAR; PG8_SCHED;
;             PG8_LDB(B0, 1, 0); PG8_LDB(B1, 1, 1); PG8_SCHED; PG8_LDA(At, 1, 0); PG8_STAGE(PG8_SA(0, 1), a2 + hstepA, voffA);
;             PG8_WAIT_V(8); PG8_WAIT_L(0); PG8_BAR; PG8_MMA(0, 0, At, B0); PG8_MMA(0, 1, At, B1); PG8_BAR; PG8_SCHED;
	s_waitcnt lgkmcnt(0)
	v_mfma_f32_16x16x32_bf16 v[60:63], v[130:133], v[178:181], v[60:63]
	v_mfma_f32_16x16x32_bf16 v[56:59], v[150:153], v[178:181], v[56:59]
	v_mfma_f32_16x16x32_bf16 v[44:47], v[130:133], v[186:189], v[44:47]
	v_mfma_f32_16x16x32_bf16 v[40:43], v[150:153], v[186:189], v[40:43]
	v_mfma_f32_16x16x32_bf16 v[28:31], v[130:133], v[194:197], v[28:31]
	v_mfma_f32_16x16x32_bf16 v[24:27], v[150:153], v[194:197], v[24:27]
	v_mfma_f32_16x16x32_bf16 v[12:15], v[130:133], v[202:205], v[12:15]
	v_mfma_f32_16x16x32_bf16 v[8:11], v[150:153], v[202:205], v[8:11]
	v_mfma_f32_16x16x32_bf16 v[60:63], v[146:149], v[182:185], v[60:63]
	v_mfma_f32_16x16x32_bf16 v[56:59], v[158:161], v[182:185], v[56:59]
	v_mfma_f32_16x16x32_bf16 v[44:47], v[146:149], v[190:193], v[44:47]
	v_mfma_f32_16x16x32_bf16 v[40:43], v[158:161], v[190:193], v[40:43]
	v_mfma_f32_16x16x32_bf16 v[28:31], v[146:149], v[198:201], v[28:31]
	v_mfma_f32_16x16x32_bf16 v[24:27], v[158:161], v[198:201], v[24:27]
	v_mfma_f32_16x16x32_bf16 v[12:15], v[146:149], v[206:209], v[12:15]
	v_mfma_f32_16x16x32_bf16 v[8:11], v[158:161], v[206:209], v[8:11]
	v_mfma_f32_16x16x32_bf16 v[52:55], v[162:165], v[178:181], v[52:55]
	v_mfma_f32_16x16x32_bf16 v[48:51], v[170:173], v[178:181], v[48:51]
	v_mfma_f32_16x16x32_bf16 v[36:39], v[162:165], v[186:189], v[36:39]
	v_mfma_f32_16x16x32_bf16 v[32:35], v[170:173], v[186:189], v[32:35]
	v_mfma_f32_16x16x32_bf16 v[20:23], v[162:165], v[194:197], v[20:23]
	v_mfma_f32_16x16x32_bf16 v[16:19], v[170:173], v[194:197], v[16:19]
	v_mfma_f32_16x16x32_bf16 v[4:7], v[162:165], v[202:205], v[4:7]
	v_mfma_f32_16x16x32_bf16 v[0:3], v[170:173], v[202:205], v[0:3]
	v_mfma_f32_16x16x32_bf16 v[52:55], v[166:169], v[182:185], v[52:55]
	v_mfma_f32_16x16x32_bf16 v[48:51], v[174:177], v[182:185], v[48:51]
	v_mfma_f32_16x16x32_bf16 v[36:39], v[166:169], v[190:193], v[36:39]
	v_mfma_f32_16x16x32_bf16 v[32:35], v[174:177], v[190:193], v[32:35]
	v_mfma_f32_16x16x32_bf16 v[20:23], v[166:169], v[198:201], v[20:23]
	v_mfma_f32_16x16x32_bf16 v[16:19], v[174:177], v[198:201], v[16:19]
	v_mfma_f32_16x16x32_bf16 v[4:7], v[166:169], v[206:209], v[4:7]
	v_mfma_f32_16x16x32_bf16 v[0:3], v[174:177], v[206:209], v[0:3]
	s_barrier
	s_add_i32 s13, 0, 0x18000
	v_add_u32_e32 v157, s13, v97
	s_add_i32 s16, 0, 0x1c000
	ds_read_b128 v[130:133], v157
	ds_read_b128 v[146:149], v157 offset:1024
	ds_read_b128 v[150:153], v157 offset:2048
	ds_read_b128 v[158:161], v157 offset:3072
	v_add_u32_e32 v157, s16, v97
	ds_read_b128 v[162:165], v157
	ds_read_b128 v[166:169], v157 offset:1024
	ds_read_b128 v[170:173], v157 offset:2048
	ds_read_b128 v[174:177], v157 offset:3072
	s_add_u32 s6, s6, s48
	s_addc_u32 s7, s7, s49
	s_mov_b32 m0, s92
	v_lshl_add_u64 v[228:229], s[6:7], 0, v[134:135]
	ds_read_b128 v[178:181], v156 offset:32768
	ds_read_b128 v[182:185], v156 offset:33792
	ds_read_b128 v[186:189], v156 offset:34816
	ds_read_b128 v[190:193], v156 offset:35840
	ds_read_b128 v[194:197], v156 offset:36864
	ds_read_b128 v[198:201], v156 offset:37888
	ds_read_b128 v[202:205], v156 offset:38912
	ds_read_b128 v[206:209], v156 offset:39936
	global_load_lds_dwordx4 v[228:229], off
	v_lshl_add_u64 v[228:229], s[6:7], 0, v[138:139]
	s_mov_b32 m0, s93
	s_nop 0
	global_load_lds_dwordx4 v[228:229], off
	s_waitcnt vmcnt(8)
	s_waitcnt lgkmcnt(0)
	s_barrier
	s_waitcnt lgkmcnt(0)
	v_mfma_f32_16x16x32_bf16 v[126:129], v[130:133], v[178:181], v[126:129]
	v_mfma_f32_16x16x32_bf16 v[122:125], v[150:153], v[178:181], v[122:125]
	v_mfma_f32_16x16x32_bf16 v[110:113], v[130:133], v[186:189], v[110:113]
	v_mfma_f32_16x16x32_bf16 v[106:109], v[150:153], v[186:189], v[106:109]
	v_mfma_f32_16x16x32_bf16 v[92:95], v[130:133], v[194:197], v[92:95]
	v_mfma_f32_16x16x32_bf16 v[88:91], v[150:153], v[194:197], v[88:91]
	v_mfma_f32_16x16x32_bf16 v[76:79], v[130:133], v[202:205], v[76:79]
	v_mfma_f32_16x16x32_bf16 v[72:75], v[150:153], v[202:205], v[72:75]
	v_mfma_f32_16x16x32_bf16 v[126:129], v[146:149], v[182:185], v[126:129]
	v_mfma_f32_16x16x32_bf16 v[122:125], v[158:161], v[182:185], v[122:125]
	v_mfma_f32_16x16x32_bf16 v[110:113], v[146:149], v[190:193], v[110:113]
	v_mfma_f32_16x16x32_bf16 v[106:109], v[158:161], v[190:193], v[106:109]
	v_mfma_f32_16x16x32_bf16 v[92:95], v[146:149], v[198:201], v[92:95]
	v_mfma_f32_16x16x32_bf16 v[88:91], v[158:161], v[198:201], v[88:91]
	v_mfma_f32_16x16x32_bf16 v[76:79], v[146:149], v[206:209], v[76:79]
	v_mfma_f32_16x16x32_bf16 v[72:75], v[158:161], v[206:209], v[72:75]
	v_mfma_f32_16x16x32_bf16 v[118:121], v[162:165], v[178:181], v[118:121]
	v_mfma_f32_16x16x32_bf16 v[114:117], v[170:173], v[178:181], v[114:117]
	v_mfma_f32_16x16x32_bf16 v[102:105], v[162:165], v[186:189], v[102:105]
	v_mfma_f32_16x16x32_bf16 v[98:101], v[170:173], v[186:189], v[98:101]
	v_mfma_f32_16x16x32_bf16 v[84:87], v[162:165], v[194:197], v[84:87]
	v_mfma_f32_16x16x32_bf16 v[80:83], v[170:173], v[194:197], v[80:83]
	v_mfma_f32_16x16x32_bf16 v[68:71], v[162:165], v[202:205], v[68:71]
	v_mfma_f32_16x16x32_bf16 v[64:67], v[170:173], v[202:205], v[64:67]
	v_mfma_f32_16x16x32_bf16 v[118:121], v[166:169], v[182:185], v[118:121]
	v_mfma_f32_16x16x32_bf16 v[114:117], v[174:177], v[182:185], v[114:117]
	v_mfma_f32_16x16x32_bf16 v[102:105], v[166:169], v[190:193], v[102:105]
	v_mfma_f32_16x16x32_bf16 v[98:101], v[174:177], v[190:193], v[98:101]
	v_mfma_f32_16x16x32_bf16 v[84:87], v[166:169], v[198:201], v[84:87]
	v_mfma_f32_16x16x32_bf16 v[80:83], v[174:177], v[198:201], v[80:83]
	v_mfma_f32_16x16x32_bf16 v[68:71], v[166:169], v[206:209], v[68:71]
	v_mfma_f32_16x16x32_bf16 v[64:67], v[174:177], v[206:209], v[64:67]
	s_barrier
; #define PG8_STAGE(bufoff, gbase, voff) do { _Pragma("unroll") for (int _i = 0; _i < 2; ++_i) \
;         __builtin_amdgcn_global_load_lds((const unsigned*)((const char*)(gbase) + (voff)[_i]), (PG8_LAS unsigned*)(lds + (bufoff) + ldsw + _i * 8192), 16, 0, 0); } while (0)
; #define PG8_LDA(dst, b, h) do { _Pragma("unroll") for (int m = 0; m < 4; ++m) _Pragma("unroll") for (int k = 0; k < 2; ++k) dst[m][k] = *(const PG8_LAS bf16x8*)(lds + PG8_SA(b, h) + aoff + m * 2048 + k * 1024); } while (0)
; #define PG8_MMA(ai, bj, At, Bt) do { __builtin_amdgcn_s_setprio(1); _Pragma("unroll") for (int m = 0; m < 4; ++m) _Pragma("unroll") for (int n = 0; n < 2; ++n) _Pragma("unroll") for (int k = 0; k < 2; ++k) \
;         acc[ai][bj][m][n] = __builtin_amdgcn_mfma_f32_16x16x32_bf16(Bt[n][k], At[m][k], acc[ai][bj][m][n], 0, 0, 0); __builtin_amdgcn_s_setprio(0); } while (0)
; #define PG8_WAIT_V(n) asm volatile("s_waitcnt vmcnt(" #n ")" ::: "memory")
; #define PG8_WAIT_L(n) asm volatile("s_waitcnt lgkmcnt(" #n ")" ::: "memory")
; #define PG8_BAR __builtin_amdgcn_s_barrier()
; #define PG8_SCHED __builtin_amdgcn_sched_barrier(0)
; template <class Epi>
; __device__ __forceinline__ void gemm_phase(PG8_LAS unsigned char* lds, const Gemm g, const StaticOrder& S, const Epi& E, const int wave_s) {
;     ...
;             PG8_LDA(At, 1, 1); PG8_STAGE(PG8_SB(1, 0), b3, voffB); PG8_STAGE(PG8_SB(1, 1), b3 + hstepB, voffB); PG8_STAGE(PG8_SA(1, 0), a3, voffA);
;             PG8_WAIT_V(8); PG8_WAIT_L(0); PG8_BAR; PG8_MMA(1, 0, At, B0); PG8_MMA(1, 1, At, B1); PG8_BAR; PG8_SCHED;
;         }
	s_add_i32 s6, s13, s37
	v_lshl_add_u64 v[154:155], v[154:155], 0, s[52:53]
	s_mov_b32 m0, s6
	ds_read_b128 v[178:181], v156 offset:49152
	ds_read_b128 v[182:185], v156 offset:50176
	ds_read_b128 v[186:189], v156 offset:51200
	ds_read_b128 v[190:193], v156 offset:52224
	ds_read_b128 v[194:197], v156 offset:53248
	ds_read_b128 v[198:201], v156 offset:54272
	ds_read_b128 v[202:205], v156 offset:55296
	ds_read_b128 v[206:209], v156 offset:56320
	global_load_lds_dwordx4 v[154:155], off
	v_lshl_add_u64 v[154:155], v[218:219], 0, s[52:53]
	s_add_i32 m0, s6, 0x2000
	s_add_i32 s6, s16, s37
	global_load_lds_dwordx4 v[154:155], off
	v_lshl_add_u64 v[154:155], v[220:221], 0, s[52:53]
	s_mov_b32 m0, s6
	s_nop 0
	global_load_lds_dwordx4 v[154:155], off
	v_lshl_add_u64 v[154:155], v[222:223], 0, s[52:53]
	s_add_i32 m0, s6, 0x2000
	s_nop 0
	global_load_lds_dwordx4 v[154:155], off
	v_lshl_add_u64 v[154:155], v[224:225], 0, s[52:53]
	s_mov_b32 m0, s64
	s_nop 0
	global_load_lds_dwordx4 v[154:155], off
	v_lshl_add_u64 v[154:155], v[226:227], 0, s[52:53]
	s_mov_b32 m0, s65
	s_nop 0
	global_load_lds_dwordx4 v[154:155], off
	s_waitcnt vmcnt(8)
	s_waitcnt lgkmcnt(0)
	s_barrier
	s_waitcnt lgkmcnt(0)
	v_mfma_f32_16x16x32_bf16 v[60:63], v[130:133], v[178:181], v[60:63]
	v_mfma_f32_16x16x32_bf16 v[56:59], v[150:153], v[178:181], v[56:59]
	s_add_u32 s44, s44, 0x100
	s_addc_u32 s45, s45, 0
	s_add_u32 s8, s8, 0x100
	s_addc_u32 s9, s9, 0
	s_mov_b32 s6, s12
	s_cmp_ge_i32 s12, s4
	v_mfma_f32_16x16x32_bf16 v[44:47], v[130:133], v[186:189], v[44:47]
	v_mfma_f32_16x16x32_bf16 v[40:43], v[150:153], v[186:189], v[40:43]
	v_mfma_f32_16x16x32_bf16 v[28:31], v[130:133], v[194:197], v[28:31]
	v_mfma_f32_16x16x32_bf16 v[24:27], v[150:153], v[194:197], v[24:27]
	v_mfma_f32_16x16x32_bf16 v[12:15], v[130:133], v[202:205], v[12:15]
	v_mfma_f32_16x16x32_bf16 v[8:11], v[150:153], v[202:205], v[8:11]
	v_mfma_f32_16x16x32_bf16 v[60:63], v[146:149], v[182:185], v[60:63]
	v_mfma_f32_16x16x32_bf16 v[56:59], v[158:161], v[182:185], v[56:59]
	v_mfma_f32_16x16x32_bf16 v[44:47], v[146:149], v[190:193], v[44:47]
	v_mfma_f32_16x16x32_bf16 v[40:43], v[158:161], v[190:193], v[40:43]
	v_mfma_f32_16x16x32_bf16 v[28:31], v[146:149], v[198:201], v[28:31]
	v_mfma_f32_16x16x32_bf16 v[24:27], v[158:161], v[198:201], v[24:27]
	v_mfma_f32_16x16x32_bf16 v[12:15], v[146:149], v[206:209], v[12:15]
	v_mfma_f32_16x16x32_bf16 v[8:11], v[158:161], v[206:209], v[8:11]
	v_mfma_f32_16x16x32_bf16 v[52:55], v[162:165], v[178:181], v[52:55]
	v_mfma_f32_16x16x32_bf16 v[48:51], v[170:173], v[178:181], v[48:51]
	v_mfma_f32_16x16x32_bf16 v[36:39], v[162:165], v[186:189], v[36:39]
	v_mfma_f32_16x16x32_bf16 v[32:35], v[170:173], v[186:189], v[32:35]
	v_mfma_f32_16x16x32_bf16 v[20:23], v[162:165], v[194:197], v[20:23]
	v_mfma_f32_16x16x32_bf16 v[16:19], v[170:173], v[194:197], v[16:19]
	v_mfma_f32_16x16x32_bf16 v[4:7], v[162:165], v[202:205], v[4:7]
	v_mfma_f32_16x16x32_bf16 v[0:3], v[170:173], v[202:205], v[0:3]
	v_mfma_f32_16x16x32_bf16 v[52:55], v[166:169], v[182:185], v[52:55]
	v_mfma_f32_16x16x32_bf16 v[48:51], v[174:177], v[182:185], v[48:51]
	v_mfma_f32_16x16x32_bf16 v[36:39], v[166:169], v[190:193], v[36:39]
	v_mfma_f32_16x16x32_bf16 v[32:35], v[174:177], v[190:193], v[32:35]
	v_mfma_f32_16x16x32_bf16 v[20:23], v[166:169], v[198:201], v[20:23]
	v_mfma_f32_16x16x32_bf16 v[16:19], v[174:177], v[198:201], v[16:19]
	v_mfma_f32_16x16x32_bf16 v[4:7], v[166:169], v[206:209], v[4:7]
	v_mfma_f32_16x16x32_bf16 v[0:3], v[174:177], v[206:209], v[0:3]
	s_barrier
	s_cbranch_scc0 .LBB0_459
	s_setprio 0
	v_readlane_b32 s38, v255, 5
	v_readlane_b32 s39, v255, 6

; #define PG8_STAGE(bufoff, gbase, voff) do { _Pragma("unroll") for (int _i = 0; _i < 2; ++_i) \
;         __builtin_amdgcn_global_load_lds((const unsigned*)((const char*)(gbase) + (voff)[_i]), (PG8_LAS unsigned*)(lds + (bufoff) + ldsw + _i * 8192), 16, 0, 0); } while (0)
; #define PG8_LDA(dst, b, h) do { _Pragma("unroll") for (int m = 0; m < 4; ++m) _Pragma("unroll") for (int k = 0; k < 2; ++k) dst[m][k] = *(const PG8_LAS bf16x8*)(lds + PG8_SA(b, h) + aoff + m * 2048 + k * 1024); } while (0)
; #define PG8_LDB(dst, b, h) do { _Pragma("unroll") for (int n = 0; n < 2; ++n) _Pragma("unroll") for (int k = 0; k < 2; ++k) dst[n][k] = *(const PG8_LAS bf16x8*)(lds + PG8_SB(b, h) + boff + n * 2048 + k * 1024); } while (0)
; #define PG8_MMA(ai, bj, At, Bt) do { __builtin_amdgcn_s_setprio(1); _Pragma("unroll") for (int m = 0; m < 4; ++m) _Pragma("unroll") for (int n = 0; n < 2; ++n) _Pragma("unroll") for (int k = 0; k < 2; ++k) \
;         acc[ai][bj][m][n] = __builtin_amdgcn_mfma_f32_16x16x32_bf16(Bt[n][k], At[m][k], acc[ai][bj][m][n], 0, 0, 0); __builtin_amdgcn_s_setprio(0); } while (0)
; #define PG8_WAIT_V(n) asm volatile("s_waitcnt vmcnt(" #n ")" ::: "memory")
; #define PG8_WAIT_L(n) asm volatile("s_waitcnt lgkmcnt(" #n ")" ::: "memory")
; #define PG8_BAR __builtin_amdgcn_s_barrier()
; #define PG8_SCHED __builtin_amdgcn_sched_barrier(0)
; template <class Epi>
; __device__ __forceinline__ void gemm_phase(PG8_LAS unsigned char* lds, const Gemm g, const StaticOrder& S, const Epi& E, const int wave_s) {
;     ...
;         for (int t = 0; t < nt; t += 2) {
;             const bool last = (t == nt - 2);
;             const char* a1 = cA + (size_t)(t + 1) * kstep;
;             const char* a2 = last ? nA : cA + (size_t)(t + 2) * kstep; const char* b2 = last ? nB : cB + (size_t)(t + 2) * kstep;
;             const char* a3 = a2 + kstep; const char* b3 = b2 + kstep;
;             PG8_LDB(B0, 0, 0); PG8_LDB(B1, 0, 1); PG8_SCHED; PG8_LDA(At, 0, 0); PG8_STAGE(PG8_SA(1, 1), a1 + hstepA, voffA);
;             PG8_WAIT_V(8); PG8_WAIT_L(0); PG8_BAR; PG8_MMA(0, 0, At, B0); PG8_MMA(0, 1, At, B1); PG8_BAR; PG8_SCHED;
;             PG8_LDA(At, 0, 1); PG8_STAGE(PG8_SB(0, 0), b2, voffB); PG8_STAGE(PG8_SB(0, 1), b2 + hstepB, voffB); PG8_STAGE(PG8_SA(0, 0), a2, voffA);
;             PG8_WAIT_V(8); PG8_WAIT_L(0); PG8_BAR; PG8_MMA(1, 0, At, B0); PG8_MMA(1, 1, At, B1); PG8_BAR; PG8_SCHED;
.Lg3_prio_done:
.LBB0_651:
	s_add_i32 s48, s6, 2
	s_add_u32 s49, s44, 0x80
	s_addc_u32 s7, s45, 0
	s_add_i32 s72, 0, 0x10000
	s_cmp_eq_u32 s37, s6
	s_cselect_b32 s7, s87, s7
	s_cselect_b32 s6, s86, s49
	v_add_u32_e32 v97, s72, v159
	s_cselect_b32 s51, s89, s47
	s_cselect_b32 s50, s88, s46
	s_add_i32 s49, 0, 0x14000
	ds_read_b128 v[150:153], v97
	ds_read_b128 v[154:157], v97 offset:1024
	ds_read_b128 v[162:165], v97 offset:2048
	ds_read_b128 v[166:169], v97 offset:3072
	v_add_u32_e32 v97, s49, v159
	ds_read_b128 v[170:173], v97
	ds_read_b128 v[174:177], v97 offset:1024
	ds_read_b128 v[178:181], v97 offset:2048
	ds_read_b128 v[182:185], v97 offset:3072
	v_lshl_add_u64 v[226:227], s[44:45], 0, v[140:141]
	s_add_i32 m0, s8, 0xc000
	ds_read_b128 v[186:189], v160
	ds_read_b128 v[190:193], v160 offset:1024
	ds_read_b128 v[194:197], v160 offset:2048
	ds_read_b128 v[198:201], v160 offset:3072
	ds_read_b128 v[202:205], v160 offset:4096
	ds_read_b128 v[206:209], v160 offset:5120
	ds_read_b128 v[218:221], v160 offset:6144
	ds_read_b128 v[222:225], v160 offset:7168
	global_load_lds_dwordx4 v[226:227], off
	v_lshl_add_u64 v[226:227], s[44:45], 0, v[142:143]
	s_add_i32 m0, s8, 0xe000
	s_nop 0
	global_load_lds_dwordx4 v[226:227], off
	s_waitcnt vmcnt(8)
	s_waitcnt lgkmcnt(0)
	s_barrier
	s_waitcnt lgkmcnt(0)
	v_mfma_f32_16x16x32_bf16 v[130:133], v[150:153], v[186:189], v[130:133]
	v_mfma_f32_16x16x32_bf16 v[126:129], v[162:165], v[186:189], v[126:129]
	v_mfma_f32_16x16x32_bf16 v[114:117], v[150:153], v[194:197], v[114:117]
	v_mfma_f32_16x16x32_bf16 v[110:113], v[162:165], v[194:197], v[110:113]
	v_mfma_f32_16x16x32_bf16 v[98:101], v[150:153], v[202:205], v[98:101]
	v_mfma_f32_16x16x32_bf16 v[92:95], v[162:165], v[202:205], v[92:95]
	v_mfma_f32_16x16x32_bf16 v[80:83], v[150:153], v[218:221], v[80:83]
	v_mfma_f32_16x16x32_bf16 v[76:79], v[162:165], v[218:221], v[76:79]
	v_mfma_f32_16x16x32_bf16 v[130:133], v[154:157], v[190:193], v[130:133]
	v_mfma_f32_16x16x32_bf16 v[126:129], v[166:169], v[190:193], v[126:129]
	v_mfma_f32_16x16x32_bf16 v[114:117], v[154:157], v[198:201], v[114:117]
	v_mfma_f32_16x16x32_bf16 v[110:113], v[166:169], v[198:201], v[110:113]
	v_mfma_f32_16x16x32_bf16 v[98:101], v[154:157], v[206:209], v[98:101]
	v_mfma_f32_16x16x32_bf16 v[92:95], v[166:169], v[206:209], v[92:95]
	v_mfma_f32_16x16x32_bf16 v[80:83], v[154:157], v[222:225], v[80:83]
	v_mfma_f32_16x16x32_bf16 v[76:79], v[166:169], v[222:225], v[76:79]
	v_mfma_f32_16x16x32_bf16 v[122:125], v[170:173], v[186:189], v[122:125]
	v_mfma_f32_16x16x32_bf16 v[118:121], v[178:181], v[186:189], v[118:121]
	v_mfma_f32_16x16x32_bf16 v[106:109], v[170:173], v[194:197], v[106:109]
	v_mfma_f32_16x16x32_bf16 v[102:105], v[178:181], v[194:197], v[102:105]
	v_mfma_f32_16x16x32_bf16 v[88:91], v[170:173], v[202:205], v[88:91]
	v_mfma_f32_16x16x32_bf16 v[84:87], v[178:181], v[202:205], v[84:87]
	v_mfma_f32_16x16x32_bf16 v[72:75], v[170:173], v[218:221], v[72:75]
	v_mfma_f32_16x16x32_bf16 v[68:71], v[178:181], v[218:221], v[68:71]
	v_mfma_f32_16x16x32_bf16 v[122:125], v[174:177], v[190:193], v[122:125]
	v_mfma_f32_16x16x32_bf16 v[118:121], v[182:185], v[190:193], v[118:121]
	v_mfma_f32_16x16x32_bf16 v[106:109], v[174:177], v[198:201], v[106:109]
	v_mfma_f32_16x16x32_bf16 v[102:105], v[182:185], v[198:201], v[102:105]
	v_mfma_f32_16x16x32_bf16 v[88:91], v[174:177], v[206:209], v[88:91]
	v_mfma_f32_16x16x32_bf16 v[84:87], v[182:185], v[206:209], v[84:87]
	v_mfma_f32_16x16x32_bf16 v[72:75], v[174:177], v[222:225], v[72:75]
	v_mfma_f32_16x16x32_bf16 v[68:71], v[182:185], v[222:225], v[68:71]
	s_barrier
	s_add_i32 s72, s72, s5
	v_lshl_add_u64 v[226:227], s[50:51], 0, v[210:211]
	s_mov_b32 m0, s72
	ds_read_b128 v[186:189], v160 offset:16384
	ds_read_b128 v[190:193], v160 offset:17408
	ds_read_b128 v[194:197], v160 offset:18432
	ds_read_b128 v[198:201], v160 offset:19456
	ds_read_b128 v[202:205], v160 offset:20480
	ds_read_b128 v[206:209], v160 offset:21504
	ds_read_b128 v[218:221], v160 offset:22528
	ds_read_b128 v[222:225], v160 offset:23552
	global_load_lds_dwordx4 v[226:227], off
	s_add_i32 m0, s72, 0x2000
	v_lshl_add_u64 v[228:229], s[50:51], 0, v[138:139]
	s_add_u32 s50, s50, s60
	s_addc_u32 s51, s51, s61
	s_add_i32 s49, s49, s5
	global_load_lds_dwordx4 v[228:229], off
	v_lshl_add_u64 v[230:231], s[50:51], 0, v[210:211]
	s_mov_b32 m0, s49
	v_lshl_add_u64 v[232:233], s[50:51], 0, v[138:139]
	global_load_lds_dwordx4 v[230:231], off
	s_add_i32 m0, s49, 0x2000
	v_lshl_add_u64 v[242:243], s[6:7], 0, v[134:135]
	global_load_lds_dwordx4 v[232:233], off
	s_mov_b32 m0, s8
	v_lshl_add_u64 v[244:245], s[6:7], 0, v[136:137]
	global_load_lds_dwordx4 v[242:243], off
	s_mov_b32 m0, s9
	s_nop 0
	global_load_lds_dwordx4 v[244:245], off
	s_waitcnt vmcnt(8)
	s_waitcnt lgkmcnt(0)
	s_barrier
; #define PG8_STAGE(bufoff, gbase, voff) do { _Pragma("unroll") for (int _i = 0; _i < 2; ++_i) \
;         __builtin_amdgcn_global_load_lds((const unsigned*)((const char*)(gbase) + (voff)[_i]), (PG8_LAS unsigned*)(lds + (bufoff) + ldsw + _i * 8192), 16, 0, 0); } while (0)
; #define PG8_LDA(dst, b, h) do { _Pragma("unroll") for (int m = 0; m < 4; ++m) _Pragma("unroll") for (int k = 0; k < 2; ++k) dst[m][k] = *(const PG8_LAS bf16x8*)(lds + PG8_SA(b, h) + aoff + m * 2048 + k * 1024); } while (0)
; #define PG8_LDB(dst, b, h) do { _Pragma("unroll") for (int n = 0; n < 2; ++n) _Pragma("unroll") for (int k = 0; k < 2; ++k) dst[n][k] = *(const PG8_LAS bf16x8*)(lds + PG8_SB(b, h) + boff + n * 2048 + k * 1024); } while (0)
; #define PG8_MMA(ai, bj, At, Bt) do { __builtin_amdgcn_s_setprio(1); _Pragma("unroll") for (int m = 0; m < 4; ++m) _Pragma("unroll") for (int n = 0; n < 2; ++n) _Pragma("unroll") for (int k = 0; k < 2; ++k) \
;         acc[ai][bj][m][n] = __builtin_amdgcn_mfma_f32_16x16x32_bf16(Bt[n][k], At[m][k], acc[ai][bj][m][n], 0, 0, 0); __builtin_amdgcn_s_setprio(0); } while (0)
; #define PG8_WAIT_V(n) asm volatile("s_waitcnt vmcnt(" #n ")" ::: "memory")
; #define PG8_WAIT_L(n) asm volatile("s_waitcnt lgkmcnt(" #n ")" ::: "memory")
; #define PG8_BAR __builtin_amdgcn_s_barrier()
; #define PG8_SCHED __builtin_amdgcn_sched_barrier(0)
; template <class Epi>
; __device__ __forceinline__ void gemm_phase(PG8_LAS unsigned char* lds, const Gemm g, const StaticOrder& S, const Epi& E, const int wave_s) {
;     ...
;             PG8_WAIT_V(8); PG8_WAIT_L(0); PG8_BAR; PG8_MMA(1, 0, At, B0); PG8_MMA(1, 1, At, B1); PG8_BAR; PG8_SCHED;
;             PG8_LDB(B0, 1, 0); PG8_LDB(B1, 1, 1); PG8_SCHED; PG8_LDA(At, 1, 0); PG8_STAGE(PG8_SA(0, 1), a2 + hstepA, voffA);
;             PG8_WAIT_V(8); PG8_WAIT_L(0); PG8_BAR; PG8_MMA(0, 0, At, B0); PG8_MMA(0, 1, At, B1); PG8_BAR; PG8_SCHED;
	s_waitcnt lgkmcnt(0)
	v_mfma_f32_16x16x32_bf16 v[64:67], v[150:153], v[186:189], v[64:67]
	v_mfma_f32_16x16x32_bf16 v[60:63], v[162:165], v[186:189], v[60:63]
	v_mfma_f32_16x16x32_bf16 v[48:51], v[150:153], v[194:197], v[48:51]
	v_mfma_f32_16x16x32_bf16 v[44:47], v[162:165], v[194:197], v[44:47]
	v_mfma_f32_16x16x32_bf16 v[32:35], v[150:153], v[202:205], v[32:35]
	v_mfma_f32_16x16x32_bf16 v[28:31], v[162:165], v[202:205], v[28:31]
	v_mfma_f32_16x16x32_bf16 v[16:19], v[150:153], v[218:221], v[16:19]
	v_mfma_f32_16x16x32_bf16 v[12:15], v[162:165], v[218:221], v[12:15]
	v_mfma_f32_16x16x32_bf16 v[64:67], v[154:157], v[190:193], v[64:67]
	v_mfma_f32_16x16x32_bf16 v[60:63], v[166:169], v[190:193], v[60:63]
	v_mfma_f32_16x16x32_bf16 v[48:51], v[154:157], v[198:201], v[48:51]
	v_mfma_f32_16x16x32_bf16 v[44:47], v[166:169], v[198:201], v[44:47]
	v_mfma_f32_16x16x32_bf16 v[32:35], v[154:157], v[206:209], v[32:35]
	v_mfma_f32_16x16x32_bf16 v[28:31], v[166:169], v[206:209], v[28:31]
	v_mfma_f32_16x16x32_bf16 v[16:19], v[154:157], v[222:225], v[16:19]
	v_mfma_f32_16x16x32_bf16 v[12:15], v[166:169], v[222:225], v[12:15]
	v_mfma_f32_16x16x32_bf16 v[56:59], v[170:173], v[186:189], v[56:59]
	v_mfma_f32_16x16x32_bf16 v[52:55], v[178:181], v[186:189], v[52:55]
	v_mfma_f32_16x16x32_bf16 v[40:43], v[170:173], v[194:197], v[40:43]
	v_mfma_f32_16x16x32_bf16 v[36:39], v[178:181], v[194:197], v[36:39]
	v_mfma_f32_16x16x32_bf16 v[24:27], v[170:173], v[202:205], v[24:27]
	v_mfma_f32_16x16x32_bf16 v[20:23], v[178:181], v[202:205], v[20:23]
	v_mfma_f32_16x16x32_bf16 v[8:11], v[170:173], v[218:221], v[8:11]
	v_mfma_f32_16x16x32_bf16 v[4:7], v[178:181], v[218:221], v[4:7]
	v_mfma_f32_16x16x32_bf16 v[56:59], v[174:177], v[190:193], v[56:59]
	v_mfma_f32_16x16x32_bf16 v[52:55], v[182:185], v[190:193], v[52:55]
	v_mfma_f32_16x16x32_bf16 v[40:43], v[174:177], v[198:201], v[40:43]
	v_mfma_f32_16x16x32_bf16 v[36:39], v[182:185], v[198:201], v[36:39]
	v_mfma_f32_16x16x32_bf16 v[24:27], v[174:177], v[206:209], v[24:27]
	v_mfma_f32_16x16x32_bf16 v[20:23], v[182:185], v[206:209], v[20:23]
	v_mfma_f32_16x16x32_bf16 v[8:11], v[174:177], v[222:225], v[8:11]
	v_mfma_f32_16x16x32_bf16 v[4:7], v[182:185], v[222:225], v[4:7]
	s_barrier
	s_add_i32 s49, 0, 0x18000
	v_add_u32_e32 v97, s49, v159
	s_add_i32 s50, 0, 0x1c000
	ds_read_b128 v[150:153], v97
	ds_read_b128 v[154:157], v97 offset:1024
	ds_read_b128 v[162:165], v97 offset:2048
	ds_read_b128 v[166:169], v97 offset:3072
	v_add_u32_e32 v97, s50, v159
	ds_read_b128 v[170:173], v97
	ds_read_b128 v[174:177], v97 offset:1024
	ds_read_b128 v[178:181], v97 offset:2048
	ds_read_b128 v[182:185], v97 offset:3072
	s_add_u32 s6, s6, s20
	s_addc_u32 s7, s7, s21
	s_mov_b32 m0, s10
	v_lshl_add_u64 v[246:247], s[6:7], 0, v[134:135]
	ds_read_b128 v[186:189], v160 offset:32768
	ds_read_b128 v[190:193], v160 offset:33792
	ds_read_b128 v[194:197], v160 offset:34816
	ds_read_b128 v[198:201], v160 offset:35840
	ds_read_b128 v[202:205], v160 offset:36864
	ds_read_b128 v[206:209], v160 offset:37888
	ds_read_b128 v[218:221], v160 offset:38912
	ds_read_b128 v[222:225], v160 offset:39936
	global_load_lds_dwordx4 v[246:247], off
	v_lshl_add_u64 v[246:247], s[6:7], 0, v[136:137]
	s_mov_b32 m0, s11
	s_nop 0
	global_load_lds_dwordx4 v[246:247], off
	s_waitcnt vmcnt(8)
	s_waitcnt lgkmcnt(0)
	s_barrier
	s_waitcnt lgkmcnt(0)
	v_mfma_f32_16x16x32_bf16 v[130:133], v[150:153], v[186:189], v[130:133]
	v_mfma_f32_16x16x32_bf16 v[126:129], v[162:165], v[186:189], v[126:129]
	v_mfma_f32_16x16x32_bf16 v[114:117], v[150:153], v[194:197], v[114:117]
	v_mfma_f32_16x16x32_bf16 v[110:113], v[162:165], v[194:197], v[110:113]
	v_mfma_f32_16x16x32_bf16 v[98:101], v[150:153], v[202:205], v[98:101]
	v_mfma_f32_16x16x32_bf16 v[92:95], v[162:165], v[202:205], v[92:95]
	v_mfma_f32_16x16x32_bf16 v[80:83], v[150:153], v[218:221], v[80:83]
	v_mfma_f32_16x16x32_bf16 v[76:79], v[162:165], v[218:221], v[76:79]
	v_mfma_f32_16x16x32_bf16 v[130:133], v[154:157], v[190:193], v[130:133]
	v_mfma_f32_16x16x32_bf16 v[126:129], v[166:169], v[190:193], v[126:129]
	v_mfma_f32_16x16x32_bf16 v[114:117], v[154:157], v[198:201], v[114:117]
	v_mfma_f32_16x16x32_bf16 v[110:113], v[166:169], v[198:201], v[110:113]
	v_mfma_f32_16x16x32_bf16 v[98:101], v[154:157], v[206:209], v[98:101]
	v_mfma_f32_16x16x32_bf16 v[92:95], v[166:169], v[206:209], v[92:95]
	v_mfma_f32_16x16x32_bf16 v[80:83], v[154:157], v[222:225], v[80:83]
	v_mfma_f32_16x16x32_bf16 v[76:79], v[166:169], v[222:225], v[76:79]
	v_mfma_f32_16x16x32_bf16 v[122:125], v[170:173], v[186:189], v[122:125]
	v_mfma_f32_16x16x32_bf16 v[118:121], v[178:181], v[186:189], v[118:121]
	v_mfma_f32_16x16x32_bf16 v[106:109], v[170:173], v[194:197], v[106:109]
	v_mfma_f32_16x16x32_bf16 v[102:105], v[178:181], v[194:197], v[102:105]
	v_mfma_f32_16x16x32_bf16 v[88:91], v[170:173], v[202:205], v[88:91]
	v_mfma_f32_16x16x32_bf16 v[84:87], v[178:181], v[202:205], v[84:87]
	v_mfma_f32_16x16x32_bf16 v[72:75], v[170:173], v[218:221], v[72:75]
	v_mfma_f32_16x16x32_bf16 v[68:71], v[178:181], v[218:221], v[68:71]
	v_mfma_f32_16x16x32_bf16 v[122:125], v[174:177], v[190:193], v[122:125]
	v_mfma_f32_16x16x32_bf16 v[118:121], v[182:185], v[190:193], v[118:121]
	v_mfma_f32_16x16x32_bf16 v[106:109], v[174:177], v[198:201], v[106:109]
	v_mfma_f32_16x16x32_bf16 v[102:105], v[182:185], v[198:201], v[102:105]
	v_mfma_f32_16x16x32_bf16 v[88:91], v[174:177], v[206:209], v[88:91]
	v_mfma_f32_16x16x32_bf16 v[84:87], v[182:185], v[206:209], v[84:87]
	v_mfma_f32_16x16x32_bf16 v[72:75], v[174:177], v[222:225], v[72:75]
	v_mfma_f32_16x16x32_bf16 v[68:71], v[182:185], v[222:225], v[68:71]
	s_barrier
; #define PG8_STAGE(bufoff, gbase, voff) do { _Pragma("unroll") for (int _i = 0; _i < 2; ++_i) \
;         __builtin_amdgcn_global_load_lds((const unsigned*)((const char*)(gbase) + (voff)[_i]), (PG8_LAS unsigned*)(lds + (bufoff) + ldsw + _i * 8192), 16, 0, 0); } while (0)
; #define PG8_LDA(dst, b, h) do { _Pragma("unroll") for (int m = 0; m < 4; ++m) _Pragma("unroll") for (int k = 0; k < 2; ++k) dst[m][k] = *(const PG8_LAS bf16x8*)(lds + PG8_SA(b, h) + aoff + m * 2048 + k * 1024); } while (0)
; #define PG8_MMA(ai, bj, At, Bt) do { __builtin_amdgcn_s_setprio(1); _Pragma("unroll") for (int m = 0; m < 4; ++m) _Pragma("unroll") for (int n = 0; n < 2; ++n) _Pragma("unroll") for (int k = 0; k < 2; ++k) \
;         acc[ai][bj][m][n] = __builtin_amdgcn_mfma_f32_16x16x32_bf16(Bt[n][k], At[m][k], acc[ai][bj][m][n], 0, 0, 0); __builtin_amdgcn_s_setprio(0); } while (0)
; #define PG8_WAIT_V(n) asm volatile("s_waitcnt vmcnt(" #n ")" ::: "memory")
; #define PG8_WAIT_L(n) asm volatile("s_waitcnt lgkmcnt(" #n ")" ::: "memory")
; #define PG8_BAR __builtin_amdgcn_s_barrier()
; #define PG8_SCHED __builtin_amdgcn_sched_barrier(0)
; template <class Epi>
; __device__ __forceinline__ void gemm_phase(PG8_LAS unsigned char* lds, const Gemm g, const StaticOrder& S, const Epi& E, const int wave_s) {
;     ...
;             PG8_LDA(At, 1, 1); PG8_STAGE(PG8_SB(1, 0), b3, voffB); PG8_STAGE(PG8_SB(1, 1), b3 + hstepB, voffB); PG8_STAGE(PG8_SA(1, 0), a3, voffA);
;             PG8_WAIT_V(8); PG8_WAIT_L(0); PG8_BAR; PG8_MMA(1, 0, At, B0); PG8_MMA(1, 1, At, B1); PG8_BAR; PG8_SCHED;
;         }
	s_add_i32 s6, s49, s5
	v_lshl_add_u64 v[226:227], v[226:227], 0, s[52:53]
	s_mov_b32 m0, s6
	ds_read_b128 v[186:189], v160 offset:49152
	ds_read_b128 v[190:193], v160 offset:50176
	ds_read_b128 v[194:197], v160 offset:51200
	ds_read_b128 v[198:201], v160 offset:52224
	ds_read_b128 v[202:205], v160 offset:53248
	ds_read_b128 v[206:209], v160 offset:54272
	ds_read_b128 v[218:221], v160 offset:55296
	ds_read_b128 v[222:225], v160 offset:56320
	global_load_lds_dwordx4 v[226:227], off
	v_lshl_add_u64 v[226:227], v[228:229], 0, s[52:53]
	s_add_i32 m0, s6, 0x2000
	s_add_i32 s6, s50, s5
	global_load_lds_dwordx4 v[226:227], off
	v_lshl_add_u64 v[226:227], v[230:231], 0, s[52:53]
	s_mov_b32 m0, s6
	s_nop 0
	global_load_lds_dwordx4 v[226:227], off
	v_lshl_add_u64 v[226:227], v[232:233], 0, s[52:53]
	s_add_i32 m0, s6, 0x2000
	s_nop 0
	global_load_lds_dwordx4 v[226:227], off
	v_lshl_add_u64 v[226:227], v[242:243], 0, s[52:53]
	s_mov_b32 m0, s27
	s_nop 0
	global_load_lds_dwordx4 v[226:227], off
	v_lshl_add_u64 v[226:227], v[244:245], 0, s[52:53]
	s_mov_b32 m0, s36
	s_nop 0
	global_load_lds_dwordx4 v[226:227], off
	s_waitcnt vmcnt(8)
	s_waitcnt lgkmcnt(0)
	s_barrier
	s_waitcnt lgkmcnt(0)
	v_mfma_f32_16x16x32_bf16 v[64:67], v[150:153], v[186:189], v[64:67]
	v_mfma_f32_16x16x32_bf16 v[60:63], v[162:165], v[186:189], v[60:63]
	s_add_u32 s44, s44, 0x100
	s_addc_u32 s45, s45, 0
	s_add_u32 s46, s46, 0x100
	s_addc_u32 s47, s47, 0
	s_mov_b32 s6, s48
	s_cmp_ge_i32 s48, s25
	v_mfma_f32_16x16x32_bf16 v[48:51], v[150:153], v[194:197], v[48:51]
	v_mfma_f32_16x16x32_bf16 v[44:47], v[162:165], v[194:197], v[44:47]
	v_mfma_f32_16x16x32_bf16 v[32:35], v[150:153], v[202:205], v[32:35]
	v_mfma_f32_16x16x32_bf16 v[28:31], v[162:165], v[202:205], v[28:31]
	v_mfma_f32_16x16x32_bf16 v[16:19], v[150:153], v[218:221], v[16:19]
	v_mfma_f32_16x16x32_bf16 v[12:15], v[162:165], v[218:221], v[12:15]
	v_mfma_f32_16x16x32_bf16 v[64:67], v[154:157], v[190:193], v[64:67]
	v_mfma_f32_16x16x32_bf16 v[60:63], v[166:169], v[190:193], v[60:63]
	v_mfma_f32_16x16x32_bf16 v[48:51], v[154:157], v[198:201], v[48:51]
	v_mfma_f32_16x16x32_bf16 v[44:47], v[166:169], v[198:201], v[44:47]
	v_mfma_f32_16x16x32_bf16 v[32:35], v[154:157], v[206:209], v[32:35]
	v_mfma_f32_16x16x32_bf16 v[28:31], v[166:169], v[206:209], v[28:31]
	v_mfma_f32_16x16x32_bf16 v[16:19], v[154:157], v[222:225], v[16:19]
	v_mfma_f32_16x16x32_bf16 v[12:15], v[166:169], v[222:225], v[12:15]
	v_mfma_f32_16x16x32_bf16 v[56:59], v[170:173], v[186:189], v[56:59]
	v_mfma_f32_16x16x32_bf16 v[52:55], v[178:181], v[186:189], v[52:55]
	v_mfma_f32_16x16x32_bf16 v[40:43], v[170:173], v[194:197], v[40:43]
	v_mfma_f32_16x16x32_bf16 v[36:39], v[178:181], v[194:197], v[36:39]
	v_mfma_f32_16x16x32_bf16 v[24:27], v[170:173], v[202:205], v[24:27]
	v_mfma_f32_16x16x32_bf16 v[20:23], v[178:181], v[202:205], v[20:23]
	v_mfma_f32_16x16x32_bf16 v[8:11], v[170:173], v[218:221], v[8:11]
	v_mfma_f32_16x16x32_bf16 v[4:7], v[178:181], v[218:221], v[4:7]
	v_mfma_f32_16x16x32_bf16 v[56:59], v[174:177], v[190:193], v[56:59]
	v_mfma_f32_16x16x32_bf16 v[52:55], v[182:185], v[190:193], v[52:55]
	v_mfma_f32_16x16x32_bf16 v[40:43], v[174:177], v[198:201], v[40:43]
	v_mfma_f32_16x16x32_bf16 v[36:39], v[182:185], v[198:201], v[36:39]
	v_mfma_f32_16x16x32_bf16 v[24:27], v[174:177], v[206:209], v[24:27]
	v_mfma_f32_16x16x32_bf16 v[20:23], v[182:185], v[206:209], v[20:23]
	v_mfma_f32_16x16x32_bf16 v[8:11], v[174:177], v[222:225], v[8:11]
	v_mfma_f32_16x16x32_bf16 v[4:7], v[182:185], v[222:225], v[4:7]
	s_barrier
	s_cbranch_scc0 .LBB0_651
	s_setprio 0

; #define PG8_STAGE(bufoff, gbase, voff) do { _Pragma("unroll") for (int _i = 0; _i < 2; ++_i) \
;         __builtin_amdgcn_global_load_lds((const unsigned*)((const char*)(gbase) + (voff)[_i]), (PG8_LAS unsigned*)(lds + (bufoff) + ldsw + _i * 8192), 16, 0, 0); } while (0)
; #define PG8_LDA(dst, b, h) do { _Pragma("unroll") for (int m = 0; m < 4; ++m) _Pragma("unroll") for (int k = 0; k < 2; ++k) dst[m][k] = *(const PG8_LAS bf16x8*)(lds + PG8_SA(b, h) + aoff + m * 2048 + k * 1024); } while (0)
; #define PG8_LDB(dst, b, h) do { _Pragma("unroll") for (int n = 0; n < 2; ++n) _Pragma("unroll") for (int k = 0; k < 2; ++k) dst[n][k] = *(const PG8_LAS bf16x8*)(lds + PG8_SB(b, h) + boff + n * 2048 + k * 1024); } while (0)
; #define PG8_MMA(ai, bj, At, Bt) do { __builtin_amdgcn_s_setprio(1); _Pragma("unroll") for (int m = 0; m < 4; ++m) _Pragma("unroll") for (int n = 0; n < 2; ++n) _Pragma("unroll") for (int k = 0; k < 2; ++k) \
;         acc[ai][bj][m][n] = __builtin_amdgcn_mfma_f32_16x16x32_bf16(Bt[n][k], At[m][k], acc[ai][bj][m][n], 0, 0, 0); __builtin_amdgcn_s_setprio(0); } while (0)
; #define PG8_WAIT_V(n) asm volatile("s_waitcnt vmcnt(" #n ")" ::: "memory")
; #define PG8_WAIT_L(n) asm volatile("s_waitcnt lgkmcnt(" #n ")" ::: "memory")
; #define PG8_BAR __builtin_amdgcn_s_barrier()
; #define PG8_SCHED __builtin_amdgcn_sched_barrier(0)
; template <class Epi>
; __device__ __forceinline__ void gemm_phase(PG8_LAS unsigned char* lds, const Gemm g, const StaticOrder& S, const Epi& E, const int wave_s) {
;     ...
;         for (int t = 0; t < nt; t += 2) {
;             const bool last = (t == nt - 2);
;             const char* a1 = cA + (size_t)(t + 1) * kstep;
;             const char* a2 = last ? nA : cA + (size_t)(t + 2) * kstep; const char* b2 = last ? nB : cB + (size_t)(t + 2) * kstep;
;             const char* a3 = a2 + kstep; const char* b3 = b2 + kstep;
;             PG8_LDB(B0, 0, 0); PG8_LDB(B1, 0, 1); PG8_SCHED; PG8_LDA(At, 0, 0); PG8_STAGE(PG8_SA(1, 1), a1 + hstepA, voffA);
;             PG8_WAIT_V(8); PG8_WAIT_L(0); PG8_BAR; PG8_MMA(0, 0, At, B0); PG8_MMA(0, 1, At, B1); PG8_BAR; PG8_SCHED;
;             PG8_LDA(At, 0, 1); PG8_STAGE(PG8_SB(0, 0), b2, voffB); PG8_STAGE(PG8_SB(0, 1), b2 + hstepB, voffB); PG8_STAGE(PG8_SA(0, 0), a2, voffA);
;             PG8_WAIT_V(8); PG8_WAIT_L(0); PG8_BAR; PG8_MMA(1, 0, At, B0); PG8_MMA(1, 1, At, B1); PG8_BAR; PG8_SCHED;
.Lg4_prio_done:
.LBB0_765:
	s_add_i32 s46, s6, 2
	s_add_u32 s47, s44, 0x80
	s_addc_u32 s7, s45, 0
	s_add_i32 s57, 0, 0x10000
	s_cmp_eq_u32 s92, s6
	s_cselect_b32 s7, s85, s7
	s_cselect_b32 s6, s84, s47
	s_cselect_b32 s49, s87, s13
	s_cselect_b32 s48, s86, s12
	s_add_i32 s47, 0, 0x14000
	v_add_u32_e32 v110, s57, v97
	v_add_u32_e32 v142, s47, v97
	ds_read_b128 v[98:101], v110
	ds_read_b128 v[102:105], v110 offset:1024
	ds_read_b128 v[106:109], v110 offset:2048
	ds_read_b128 v[110:113], v110 offset:3072
	ds_read_b128 v[118:121], v142
	ds_read_b128 v[122:125], v142 offset:1024
	ds_read_b128 v[138:141], v142 offset:2048
	ds_read_b128 v[142:145], v142 offset:3072
	v_lshl_add_u64 v[194:195], s[44:45], 0, v[224:225]
	s_add_i32 m0, s27, 0xc000
	ds_read_b128 v[162:165], v242
	ds_read_b128 v[166:169], v242 offset:1024
	ds_read_b128 v[170:173], v242 offset:2048
	ds_read_b128 v[174:177], v242 offset:3072
	ds_read_b128 v[178:181], v242 offset:4096
	ds_read_b128 v[182:185], v242 offset:5120
	ds_read_b128 v[186:189], v242 offset:6144
	ds_read_b128 v[190:193], v242 offset:7168
	global_load_lds_dwordx4 v[194:195], off
	v_lshl_add_u64 v[194:195], s[44:45], 0, v[226:227]
	s_add_i32 m0, s27, 0xe000
	s_nop 0
	global_load_lds_dwordx4 v[194:195], off
	s_waitcnt vmcnt(8)
	s_waitcnt lgkmcnt(0)
	s_barrier
	s_waitcnt lgkmcnt(0)
	v_mfma_f32_16x16x32_bf16 v[158:161], v[98:101], v[162:165], v[158:161]
	v_mfma_f32_16x16x32_bf16 v[154:157], v[106:109], v[162:165], v[154:157]
	v_mfma_f32_16x16x32_bf16 v[134:137], v[98:101], v[170:173], v[134:137]
	v_mfma_f32_16x16x32_bf16 v[130:133], v[106:109], v[170:173], v[130:133]
	v_mfma_f32_16x16x32_bf16 v[92:95], v[98:101], v[178:181], v[92:95]
	v_mfma_f32_16x16x32_bf16 v[88:91], v[106:109], v[178:181], v[88:91]
	v_mfma_f32_16x16x32_bf16 v[76:79], v[98:101], v[186:189], v[76:79]
	v_mfma_f32_16x16x32_bf16 v[72:75], v[106:109], v[186:189], v[72:75]
	v_mfma_f32_16x16x32_bf16 v[158:161], v[102:105], v[166:169], v[158:161]
	v_mfma_f32_16x16x32_bf16 v[154:157], v[110:113], v[166:169], v[154:157]
	v_mfma_f32_16x16x32_bf16 v[134:137], v[102:105], v[174:177], v[134:137]
	v_mfma_f32_16x16x32_bf16 v[130:133], v[110:113], v[174:177], v[130:133]
	v_mfma_f32_16x16x32_bf16 v[92:95], v[102:105], v[182:185], v[92:95]
	v_mfma_f32_16x16x32_bf16 v[88:91], v[110:113], v[182:185], v[88:91]
	v_mfma_f32_16x16x32_bf16 v[76:79], v[102:105], v[190:193], v[76:79]
	v_mfma_f32_16x16x32_bf16 v[72:75], v[110:113], v[190:193], v[72:75]
	v_mfma_f32_16x16x32_bf16 v[150:153], v[118:121], v[162:165], v[150:153]
	v_mfma_f32_16x16x32_bf16 v[146:149], v[138:141], v[162:165], v[146:149]
	v_mfma_f32_16x16x32_bf16 v[126:129], v[118:121], v[170:173], v[126:129]
	v_mfma_f32_16x16x32_bf16 v[114:117], v[138:141], v[170:173], v[114:117]
	v_mfma_f32_16x16x32_bf16 v[84:87], v[118:121], v[178:181], v[84:87]
	v_mfma_f32_16x16x32_bf16 v[80:83], v[138:141], v[178:181], v[80:83]
	v_mfma_f32_16x16x32_bf16 v[68:71], v[118:121], v[186:189], v[68:71]
	v_mfma_f32_16x16x32_bf16 v[64:67], v[138:141], v[186:189], v[64:67]
	v_mfma_f32_16x16x32_bf16 v[150:153], v[122:125], v[166:169], v[150:153]
	v_mfma_f32_16x16x32_bf16 v[146:149], v[142:145], v[166:169], v[146:149]
	v_mfma_f32_16x16x32_bf16 v[126:129], v[122:125], v[174:177], v[126:129]
	v_mfma_f32_16x16x32_bf16 v[114:117], v[142:145], v[174:177], v[114:117]
	v_mfma_f32_16x16x32_bf16 v[84:87], v[122:125], v[182:185], v[84:87]
	v_mfma_f32_16x16x32_bf16 v[80:83], v[142:145], v[182:185], v[80:83]
	v_mfma_f32_16x16x32_bf16 v[68:71], v[122:125], v[190:193], v[68:71]
	v_mfma_f32_16x16x32_bf16 v[64:67], v[142:145], v[190:193], v[64:67]
	s_barrier
	s_add_i32 s57, s57, s16
	v_lshl_add_u64 v[194:195], s[48:49], 0, v[210:211]
	s_mov_b32 m0, s57
	ds_read_b128 v[162:165], v242 offset:16384
	ds_read_b128 v[166:169], v242 offset:17408
	ds_read_b128 v[170:173], v242 offset:18432
	ds_read_b128 v[174:177], v242 offset:19456
	ds_read_b128 v[178:181], v242 offset:20480
	ds_read_b128 v[182:185], v242 offset:21504
	ds_read_b128 v[186:189], v242 offset:22528
	ds_read_b128 v[190:193], v242 offset:23552
	global_load_lds_dwordx4 v[194:195], off
	s_add_i32 m0, s57, 0x2000
	v_lshl_add_u64 v[196:197], s[48:49], 0, v[222:223]
	s_add_u32 s48, s48, s20
	s_addc_u32 s49, s49, s21
	s_add_i32 s47, s47, s16
	global_load_lds_dwordx4 v[196:197], off
	v_lshl_add_u64 v[198:199], s[48:49], 0, v[210:211]
	s_mov_b32 m0, s47
	v_lshl_add_u64 v[200:201], s[48:49], 0, v[222:223]
	global_load_lds_dwordx4 v[198:199], off
	s_add_i32 m0, s47, 0x2000
	v_lshl_add_u64 v[202:203], s[6:7], 0, v[218:219]
	global_load_lds_dwordx4 v[200:201], off
	s_mov_b32 m0, s27
	v_lshl_add_u64 v[204:205], s[6:7], 0, v[220:221]
	global_load_lds_dwordx4 v[202:203], off
	s_mov_b32 m0, s36
	s_nop 0
	global_load_lds_dwordx4 v[204:205], off
	s_waitcnt vmcnt(8)
	s_waitcnt lgkmcnt(0)
	s_barrier
; #define PG8_STAGE(bufoff, gbase, voff) do { _Pragma("unroll") for (int _i = 0; _i < 2; ++_i) \
;         __builtin_amdgcn_global_load_lds((const unsigned*)((const char*)(gbase) + (voff)[_i]), (PG8_LAS unsigned*)(lds + (bufoff) + ldsw + _i * 8192), 16, 0, 0); } while (0)
; #define PG8_LDA(dst, b, h) do { _Pragma("unroll") for (int m = 0; m < 4; ++m) _Pragma("unroll") for (int k = 0; k < 2; ++k) dst[m][k] = *(const PG8_LAS bf16x8*)(lds + PG8_SA(b, h) + aoff + m * 2048 + k * 1024); } while (0)
; #define PG8_LDB(dst, b, h) do { _Pragma("unroll") for (int n = 0; n < 2; ++n) _Pragma("unroll") for (int k = 0; k < 2; ++k) dst[n][k] = *(const PG8_LAS bf16x8*)(lds + PG8_SB(b, h) + boff + n * 2048 + k * 1024); } while (0)
; #define PG8_MMA(ai, bj, At, Bt) do { __builtin_amdgcn_s_setprio(1); _Pragma("unroll") for (int m = 0; m < 4; ++m) _Pragma("unroll") for (int n = 0; n < 2; ++n) _Pragma("unroll") for (int k = 0; k < 2; ++k) \
;         acc[ai][bj][m][n] = __builtin_amdgcn_mfma_f32_16x16x32_bf16(Bt[n][k], At[m][k], acc[ai][bj][m][n], 0, 0, 0); __builtin_amdgcn_s_setprio(0); } while (0)
; #define PG8_WAIT_V(n) asm volatile("s_waitcnt vmcnt(" #n ")" ::: "memory")
; #define PG8_WAIT_L(n) asm volatile("s_waitcnt lgkmcnt(" #n ")" ::: "memory")
; #define PG8_BAR __builtin_amdgcn_s_barrier()
; #define PG8_SCHED __builtin_amdgcn_sched_barrier(0)
; template <class Epi>
; __device__ __forceinline__ void gemm_phase(PG8_LAS unsigned char* lds, const Gemm g, const StaticOrder& S, const Epi& E, const int wave_s) {
;     ...
;             PG8_WAIT_V(8); PG8_WAIT_L(0); PG8_BAR; PG8_MMA(1, 0, At, B0); PG8_MMA(1, 1, At, B1); PG8_BAR; PG8_SCHED;
;             PG8_LDB(B0, 1, 0); PG8_LDB(B1, 1, 1); PG8_SCHED; PG8_LDA(At, 1, 0); PG8_STAGE(PG8_SA(0, 1), a2 + hstepA, voffA);
;             PG8_WAIT_V(8); PG8_WAIT_L(0); PG8_BAR; PG8_MMA(0, 0, At, B0); PG8_MMA(0, 1, At, B1); PG8_BAR; PG8_SCHED;
	s_waitcnt lgkmcnt(0)
	v_mfma_f32_16x16x32_bf16 v[60:63], v[98:101], v[162:165], v[60:63]
	v_mfma_f32_16x16x32_bf16 v[56:59], v[106:109], v[162:165], v[56:59]
	v_mfma_f32_16x16x32_bf16 v[44:47], v[98:101], v[170:173], v[44:47]
	v_mfma_f32_16x16x32_bf16 v[40:43], v[106:109], v[170:173], v[40:43]
	v_mfma_f32_16x16x32_bf16 v[28:31], v[98:101], v[178:181], v[28:31]
	v_mfma_f32_16x16x32_bf16 v[24:27], v[106:109], v[178:181], v[24:27]
	v_mfma_f32_16x16x32_bf16 v[12:15], v[98:101], v[186:189], v[12:15]
	v_mfma_f32_16x16x32_bf16 v[8:11], v[106:109], v[186:189], v[8:11]
	v_mfma_f32_16x16x32_bf16 v[60:63], v[102:105], v[166:169], v[60:63]
	v_mfma_f32_16x16x32_bf16 v[56:59], v[110:113], v[166:169], v[56:59]
	v_mfma_f32_16x16x32_bf16 v[44:47], v[102:105], v[174:177], v[44:47]
	v_mfma_f32_16x16x32_bf16 v[40:43], v[110:113], v[174:177], v[40:43]
	v_mfma_f32_16x16x32_bf16 v[28:31], v[102:105], v[182:185], v[28:31]
	v_mfma_f32_16x16x32_bf16 v[24:27], v[110:113], v[182:185], v[24:27]
	v_mfma_f32_16x16x32_bf16 v[12:15], v[102:105], v[190:193], v[12:15]
	v_mfma_f32_16x16x32_bf16 v[8:11], v[110:113], v[190:193], v[8:11]
	v_mfma_f32_16x16x32_bf16 v[52:55], v[118:121], v[162:165], v[52:55]
	v_mfma_f32_16x16x32_bf16 v[48:51], v[138:141], v[162:165], v[48:51]
	v_mfma_f32_16x16x32_bf16 v[36:39], v[118:121], v[170:173], v[36:39]
	v_mfma_f32_16x16x32_bf16 v[32:35], v[138:141], v[170:173], v[32:35]
	v_mfma_f32_16x16x32_bf16 v[20:23], v[118:121], v[178:181], v[20:23]
	v_mfma_f32_16x16x32_bf16 v[16:19], v[138:141], v[178:181], v[16:19]
	v_mfma_f32_16x16x32_bf16 v[4:7], v[118:121], v[186:189], v[4:7]
	v_mfma_f32_16x16x32_bf16 v[0:3], v[138:141], v[186:189], v[0:3]
	v_mfma_f32_16x16x32_bf16 v[52:55], v[122:125], v[166:169], v[52:55]
	v_mfma_f32_16x16x32_bf16 v[48:51], v[142:145], v[166:169], v[48:51]
	v_mfma_f32_16x16x32_bf16 v[36:39], v[122:125], v[174:177], v[36:39]
	v_mfma_f32_16x16x32_bf16 v[32:35], v[142:145], v[174:177], v[32:35]
	v_mfma_f32_16x16x32_bf16 v[20:23], v[122:125], v[182:185], v[20:23]
	v_mfma_f32_16x16x32_bf16 v[16:19], v[142:145], v[182:185], v[16:19]
	v_mfma_f32_16x16x32_bf16 v[4:7], v[122:125], v[190:193], v[4:7]
	v_mfma_f32_16x16x32_bf16 v[0:3], v[142:145], v[190:193], v[0:3]
	s_barrier
	s_add_i32 s47, 0, 0x18000
	s_add_i32 s48, 0, 0x1c000
	v_add_u32_e32 v110, s47, v97
	v_add_u32_e32 v142, s48, v97
	ds_read_b128 v[98:101], v110
	ds_read_b128 v[102:105], v110 offset:1024
	ds_read_b128 v[106:109], v110 offset:2048
	ds_read_b128 v[110:113], v110 offset:3072
	ds_read_b128 v[118:121], v142
	ds_read_b128 v[122:125], v142 offset:1024
	ds_read_b128 v[138:141], v142 offset:2048
	ds_read_b128 v[142:145], v142 offset:3072
	s_add_u32 s6, s6, s10
	s_addc_u32 s7, s7, s11
	s_mov_b32 m0, s37
	v_lshl_add_u64 v[206:207], s[6:7], 0, v[218:219]
	ds_read_b128 v[162:165], v242 offset:32768
	ds_read_b128 v[166:169], v242 offset:33792
	ds_read_b128 v[170:173], v242 offset:34816
	ds_read_b128 v[174:177], v242 offset:35840
	ds_read_b128 v[178:181], v242 offset:36864
	ds_read_b128 v[182:185], v242 offset:37888
	ds_read_b128 v[186:189], v242 offset:38912
	ds_read_b128 v[190:193], v242 offset:39936
	global_load_lds_dwordx4 v[206:207], off
	v_lshl_add_u64 v[206:207], s[6:7], 0, v[220:221]
	s_mov_b32 m0, s88
	s_nop 0
	global_load_lds_dwordx4 v[206:207], off
	s_waitcnt vmcnt(8)
	s_waitcnt lgkmcnt(0)
	s_barrier
	s_waitcnt lgkmcnt(0)
	v_mfma_f32_16x16x32_bf16 v[158:161], v[98:101], v[162:165], v[158:161]
	v_mfma_f32_16x16x32_bf16 v[154:157], v[106:109], v[162:165], v[154:157]
	v_mfma_f32_16x16x32_bf16 v[134:137], v[98:101], v[170:173], v[134:137]
	v_mfma_f32_16x16x32_bf16 v[130:133], v[106:109], v[170:173], v[130:133]
	v_mfma_f32_16x16x32_bf16 v[92:95], v[98:101], v[178:181], v[92:95]
	v_mfma_f32_16x16x32_bf16 v[88:91], v[106:109], v[178:181], v[88:91]
	v_mfma_f32_16x16x32_bf16 v[76:79], v[98:101], v[186:189], v[76:79]
	v_mfma_f32_16x16x32_bf16 v[72:75], v[106:109], v[186:189], v[72:75]
	v_mfma_f32_16x16x32_bf16 v[158:161], v[102:105], v[166:169], v[158:161]
	v_mfma_f32_16x16x32_bf16 v[154:157], v[110:113], v[166:169], v[154:157]
	v_mfma_f32_16x16x32_bf16 v[134:137], v[102:105], v[174:177], v[134:137]
	v_mfma_f32_16x16x32_bf16 v[130:133], v[110:113], v[174:177], v[130:133]
	v_mfma_f32_16x16x32_bf16 v[92:95], v[102:105], v[182:185], v[92:95]
	v_mfma_f32_16x16x32_bf16 v[88:91], v[110:113], v[182:185], v[88:91]
	v_mfma_f32_16x16x32_bf16 v[76:79], v[102:105], v[190:193], v[76:79]
	v_mfma_f32_16x16x32_bf16 v[72:75], v[110:113], v[190:193], v[72:75]
	v_mfma_f32_16x16x32_bf16 v[150:153], v[118:121], v[162:165], v[150:153]
	v_mfma_f32_16x16x32_bf16 v[146:149], v[138:141], v[162:165], v[146:149]
	v_mfma_f32_16x16x32_bf16 v[126:129], v[118:121], v[170:173], v[126:129]
	v_mfma_f32_16x16x32_bf16 v[114:117], v[138:141], v[170:173], v[114:117]
	v_mfma_f32_16x16x32_bf16 v[84:87], v[118:121], v[178:181], v[84:87]
	v_mfma_f32_16x16x32_bf16 v[80:83], v[138:141], v[178:181], v[80:83]
	v_mfma_f32_16x16x32_bf16 v[68:71], v[118:121], v[186:189], v[68:71]
	v_mfma_f32_16x16x32_bf16 v[64:67], v[138:141], v[186:189], v[64:67]
	v_mfma_f32_16x16x32_bf16 v[150:153], v[122:125], v[166:169], v[150:153]
	v_mfma_f32_16x16x32_bf16 v[146:149], v[142:145], v[166:169], v[146:149]
	v_mfma_f32_16x16x32_bf16 v[126:129], v[122:125], v[174:177], v[126:129]
	v_mfma_f32_16x16x32_bf16 v[114:117], v[142:145], v[174:177], v[114:117]
	v_mfma_f32_16x16x32_bf16 v[84:87], v[122:125], v[182:185], v[84:87]
	v_mfma_f32_16x16x32_bf16 v[80:83], v[142:145], v[182:185], v[80:83]
	v_mfma_f32_16x16x32_bf16 v[68:71], v[122:125], v[190:193], v[68:71]
	v_mfma_f32_16x16x32_bf16 v[64:67], v[142:145], v[190:193], v[64:67]
	s_barrier
; #define PG8_STAGE(bufoff, gbase, voff) do { _Pragma("unroll") for (int _i = 0; _i < 2; ++_i) \
;         __builtin_amdgcn_global_load_lds((const unsigned*)((const char*)(gbase) + (voff)[_i]), (PG8_LAS unsigned*)(lds + (bufoff) + ldsw + _i * 8192), 16, 0, 0); } while (0)
; #define PG8_LDA(dst, b, h) do { _Pragma("unroll") for (int m = 0; m < 4; ++m) _Pragma("unroll") for (int k = 0; k < 2; ++k) dst[m][k] = *(const PG8_LAS bf16x8*)(lds + PG8_SA(b, h) + aoff + m * 2048 + k * 1024); } while (0)
; #define PG8_MMA(ai, bj, At, Bt) do { __builtin_amdgcn_s_setprio(1); _Pragma("unroll") for (int m = 0; m < 4; ++m) _Pragma("unroll") for (int n = 0; n < 2; ++n) _Pragma("unroll") for (int k = 0; k < 2; ++k) \
;         acc[ai][bj][m][n] = __builtin_amdgcn_mfma_f32_16x16x32_bf16(Bt[n][k], At[m][k], acc[ai][bj][m][n], 0, 0, 0); __builtin_amdgcn_s_setprio(0); } while (0)
; #define PG8_WAIT_V(n) asm volatile("s_waitcnt vmcnt(" #n ")" ::: "memory")
; #define PG8_WAIT_L(n) asm volatile("s_waitcnt lgkmcnt(" #n ")" ::: "memory")
; #define PG8_BAR __builtin_amdgcn_s_barrier()
; #define PG8_SCHED __builtin_amdgcn_sched_barrier(0)
; template <class Epi>
; __device__ __forceinline__ void gemm_phase(PG8_LAS unsigned char* lds, const Gemm g, const StaticOrder& S, const Epi& E, const int wave_s) {
;     ...
;             PG8_LDA(At, 1, 1); PG8_STAGE(PG8_SB(1, 0), b3, voffB); PG8_STAGE(PG8_SB(1, 1), b3 + hstepB, voffB); PG8_STAGE(PG8_SA(1, 0), a3, voffA);
;             PG8_WAIT_V(8); PG8_WAIT_L(0); PG8_BAR; PG8_MMA(1, 0, At, B0); PG8_MMA(1, 1, At, B1); PG8_BAR; PG8_SCHED;
;         }
	s_add_i32 s6, s47, s16
	v_lshl_add_u64 v[194:195], v[194:195], 0, s[52:53]
	s_mov_b32 m0, s6
	ds_read_b128 v[162:165], v242 offset:49152
	ds_read_b128 v[166:169], v242 offset:50176
	ds_read_b128 v[170:173], v242 offset:51200
	ds_read_b128 v[174:177], v242 offset:52224
	ds_read_b128 v[178:181], v242 offset:53248
	ds_read_b128 v[182:185], v242 offset:54272
	ds_read_b128 v[186:189], v242 offset:55296
	ds_read_b128 v[190:193], v242 offset:56320
	global_load_lds_dwordx4 v[194:195], off
	v_lshl_add_u64 v[194:195], v[196:197], 0, s[52:53]
	s_add_i32 m0, s6, 0x2000
	s_add_i32 s6, s48, s16
	global_load_lds_dwordx4 v[194:195], off
	v_lshl_add_u64 v[194:195], v[198:199], 0, s[52:53]
	s_mov_b32 m0, s6
	s_nop 0
	global_load_lds_dwordx4 v[194:195], off
	v_lshl_add_u64 v[194:195], v[200:201], 0, s[52:53]
	s_add_i32 m0, s6, 0x2000
	s_nop 0
	global_load_lds_dwordx4 v[194:195], off
	v_lshl_add_u64 v[194:195], v[202:203], 0, s[52:53]
	s_mov_b32 m0, s93
	s_nop 0
	global_load_lds_dwordx4 v[194:195], off
	v_lshl_add_u64 v[194:195], v[204:205], 0, s[52:53]
	s_mov_b32 m0, s97
	s_nop 0
	global_load_lds_dwordx4 v[194:195], off
	s_waitcnt vmcnt(8)
	s_waitcnt lgkmcnt(0)
	s_barrier
	s_waitcnt lgkmcnt(0)
	v_mfma_f32_16x16x32_bf16 v[60:63], v[98:101], v[162:165], v[60:63]
	v_mfma_f32_16x16x32_bf16 v[56:59], v[106:109], v[162:165], v[56:59]
	s_add_u32 s44, s44, 0x100
	s_addc_u32 s45, s45, 0
	s_add_u32 s12, s12, 0x100
	s_addc_u32 s13, s13, 0
	s_mov_b32 s6, s46
	s_cmp_ge_i32 s46, s94
	v_mfma_f32_16x16x32_bf16 v[44:47], v[98:101], v[170:173], v[44:47]
	v_mfma_f32_16x16x32_bf16 v[40:43], v[106:109], v[170:173], v[40:43]
	v_mfma_f32_16x16x32_bf16 v[28:31], v[98:101], v[178:181], v[28:31]
	v_mfma_f32_16x16x32_bf16 v[24:27], v[106:109], v[178:181], v[24:27]
	v_mfma_f32_16x16x32_bf16 v[12:15], v[98:101], v[186:189], v[12:15]
	v_mfma_f32_16x16x32_bf16 v[8:11], v[106:109], v[186:189], v[8:11]
	v_mfma_f32_16x16x32_bf16 v[60:63], v[102:105], v[166:169], v[60:63]
	v_mfma_f32_16x16x32_bf16 v[56:59], v[110:113], v[166:169], v[56:59]
	v_mfma_f32_16x16x32_bf16 v[44:47], v[102:105], v[174:177], v[44:47]
	v_mfma_f32_16x16x32_bf16 v[40:43], v[110:113], v[174:177], v[40:43]
	v_mfma_f32_16x16x32_bf16 v[28:31], v[102:105], v[182:185], v[28:31]
	v_mfma_f32_16x16x32_bf16 v[24:27], v[110:113], v[182:185], v[24:27]
	v_mfma_f32_16x16x32_bf16 v[12:15], v[102:105], v[190:193], v[12:15]
	v_mfma_f32_16x16x32_bf16 v[8:11], v[110:113], v[190:193], v[8:11]
	v_mfma_f32_16x16x32_bf16 v[52:55], v[118:121], v[162:165], v[52:55]
	v_mfma_f32_16x16x32_bf16 v[48:51], v[138:141], v[162:165], v[48:51]
	v_mfma_f32_16x16x32_bf16 v[36:39], v[118:121], v[170:173], v[36:39]
	v_mfma_f32_16x16x32_bf16 v[32:35], v[138:141], v[170:173], v[32:35]
	v_mfma_f32_16x16x32_bf16 v[20:23], v[118:121], v[178:181], v[20:23]
	v_mfma_f32_16x16x32_bf16 v[16:19], v[138:141], v[178:181], v[16:19]
	v_mfma_f32_16x16x32_bf16 v[4:7], v[118:121], v[186:189], v[4:7]
	v_mfma_f32_16x16x32_bf16 v[0:3], v[138:141], v[186:189], v[0:3]
	v_mfma_f32_16x16x32_bf16 v[52:55], v[122:125], v[166:169], v[52:55]
	v_mfma_f32_16x16x32_bf16 v[48:51], v[142:145], v[166:169], v[48:51]
	v_mfma_f32_16x16x32_bf16 v[36:39], v[122:125], v[174:177], v[36:39]
	v_mfma_f32_16x16x32_bf16 v[32:35], v[142:145], v[174:177], v[32:35]
	v_mfma_f32_16x16x32_bf16 v[20:23], v[122:125], v[182:185], v[20:23]
	v_mfma_f32_16x16x32_bf16 v[16:19], v[142:145], v[182:185], v[16:19]
	v_mfma_f32_16x16x32_bf16 v[4:7], v[122:125], v[190:193], v[4:7]
	v_mfma_f32_16x16x32_bf16 v[0:3], v[142:145], v[190:193], v[0:3]
	s_barrier
	s_cbranch_scc0 .LBB0_765
	s_setprio 0

; #define PG8_STAGE(bufoff, gbase, voff) do { _Pragma("unroll") for (int _i = 0; _i < 2; ++_i) \
;         __builtin_amdgcn_global_load_lds((const unsigned*)((const char*)(gbase) + (voff)[_i]), (PG8_LAS unsigned*)(lds + (bufoff) + ldsw + _i * 8192), 16, 0, 0); } while (0)
; #define PG8_LDA(dst, b, h) do { _Pragma("unroll") for (int m = 0; m < 4; ++m) _Pragma("unroll") for (int k = 0; k < 2; ++k) dst[m][k] = *(const PG8_LAS bf16x8*)(lds + PG8_SA(b, h) + aoff + m * 2048 + k * 1024); } while (0)
; #define PG8_LDB(dst, b, h) do { _Pragma("unroll") for (int n = 0; n < 2; ++n) _Pragma("unroll") for (int k = 0; k < 2; ++k) dst[n][k] = *(const PG8_LAS bf16x8*)(lds + PG8_SB(b, h) + boff + n * 2048 + k * 1024); } while (0)
; #define PG8_MMA(ai, bj, At, Bt) do { __builtin_amdgcn_s_setprio(1); _Pragma("unroll") for (int m = 0; m < 4; ++m) _Pragma("unroll") for (int n = 0; n < 2; ++n) _Pragma("unroll") for (int k = 0; k < 2; ++k) \
;         acc[ai][bj][m][n] = __builtin_amdgcn_mfma_f32_16x16x32_bf16(Bt[n][k], At[m][k], acc[ai][bj][m][n], 0, 0, 0); __builtin_amdgcn_s_setprio(0); } while (0)
; #define PG8_WAIT_V(n) asm volatile("s_waitcnt vmcnt(" #n ")" ::: "memory")
; #define PG8_WAIT_L(n) asm volatile("s_waitcnt lgkmcnt(" #n ")" ::: "memory")
; #define PG8_BAR __builtin_amdgcn_s_barrier()
; #define PG8_SCHED __builtin_amdgcn_sched_barrier(0)
; template <class Epi>
; __device__ __forceinline__ void gemm_phase(PG8_LAS unsigned char* lds, const Gemm g, const StaticOrder& S, const Epi& E, const int wave_s) {
;     ...
;             const bool last = (t == nt - 2);
;             const char* a1 = cA + (size_t)(t + 1) * kstep;
;             const char* a2 = last ? nA : cA + (size_t)(t + 2) * kstep; const char* b2 = last ? nB : cB + (size_t)(t + 2) * kstep;
;             const char* a3 = a2 + kstep; const char* b3 = b2 + kstep;
;             PG8_LDB(B0, 0, 0); PG8_LDB(B1, 0, 1); PG8_SCHED; PG8_LDA(At, 0, 0); PG8_STAGE(PG8_SA(1, 1), a1 + hstepA, voffA);
;             PG8_WAIT_V(8); PG8_WAIT_L(0); PG8_BAR; PG8_MMA(0, 0, At, B0); PG8_MMA(0, 1, At, B1); PG8_BAR; PG8_SCHED;
;             PG8_LDA(At, 0, 1); PG8_STAGE(PG8_SB(0, 0), b2, voffB); PG8_STAGE(PG8_SB(0, 1), b2 + hstepB, voffB); PG8_STAGE(PG8_SA(0, 0), a2, voffA);
;             PG8_WAIT_V(8); PG8_WAIT_L(0); PG8_BAR; PG8_MMA(1, 0, At, B0); PG8_MMA(1, 1, At, B1); PG8_BAR; PG8_SCHED;
.Lgu_prio_done:
.LBB0_950:
	s_add_i32 s68, s6, 2
	s_add_u32 s69, s56, 0x80
	s_addc_u32 s7, s57, 0
	s_add_i32 s72, 0, 0x10000
	s_cmp_eq_u32 s60, s6
	s_cselect_b32 s7, s45, s7
	s_cselect_b32 s6, s44, s69
	v_add_u32_e32 v145, s72, v141
	s_cselect_b32 s71, s51, s67
	s_cselect_b32 s70, s50, s66
	s_add_i32 s69, 0, 0x14000
	ds_read_b128 v[156:159], v145
	ds_read_b128 v[160:163], v145 offset:1024
	ds_read_b128 v[164:167], v145 offset:2048
	ds_read_b128 v[168:171], v145 offset:3072
	v_add_u32_e32 v145, s69, v141
	ds_read_b128 v[172:175], v145
	ds_read_b128 v[176:179], v145 offset:1024
	ds_read_b128 v[180:183], v145 offset:2048
	ds_read_b128 v[184:187], v145 offset:3072
	v_lshl_add_u64 v[208:209], s[56:57], 0, v[136:137]
	s_add_i32 m0, s13, 0xc000
	ds_read_b128 v[188:191], v143
	ds_read_b128 v[192:195], v143 offset:1024
	ds_read_b128 v[196:199], v143 offset:2048
	ds_read_b128 v[200:203], v143 offset:3072
	ds_read_b128 v[204:207], v143 offset:4096
	ds_read_b128 v[218:221], v143 offset:5120
	ds_read_b128 v[222:225], v143 offset:6144
	ds_read_b128 v[226:229], v143 offset:7168
	global_load_lds_dwordx4 v[208:209], off
	v_lshl_add_u64 v[208:209], s[56:57], 0, v[138:139]
	s_add_i32 m0, s13, 0xe000
	s_nop 0
	global_load_lds_dwordx4 v[208:209], off
	s_waitcnt vmcnt(8)
	s_waitcnt lgkmcnt(0)
	s_barrier
	s_waitcnt lgkmcnt(0)
	v_mfma_f32_16x16x32_bf16 v[126:129], v[156:159], v[188:191], v[126:129]
	v_mfma_f32_16x16x32_bf16 v[122:125], v[164:167], v[188:191], v[122:125]
	v_mfma_f32_16x16x32_bf16 v[110:113], v[156:159], v[196:199], v[110:113]
	v_mfma_f32_16x16x32_bf16 v[106:109], v[164:167], v[196:199], v[106:109]
	v_mfma_f32_16x16x32_bf16 v[92:95], v[156:159], v[204:207], v[92:95]
	v_mfma_f32_16x16x32_bf16 v[88:91], v[164:167], v[204:207], v[88:91]
	v_mfma_f32_16x16x32_bf16 v[76:79], v[156:159], v[222:225], v[76:79]
	v_mfma_f32_16x16x32_bf16 v[72:75], v[164:167], v[222:225], v[72:75]
	v_mfma_f32_16x16x32_bf16 v[126:129], v[160:163], v[192:195], v[126:129]
	v_mfma_f32_16x16x32_bf16 v[122:125], v[168:171], v[192:195], v[122:125]
	v_mfma_f32_16x16x32_bf16 v[110:113], v[160:163], v[200:203], v[110:113]
	v_mfma_f32_16x16x32_bf16 v[106:109], v[168:171], v[200:203], v[106:109]
	v_mfma_f32_16x16x32_bf16 v[92:95], v[160:163], v[218:221], v[92:95]
	v_mfma_f32_16x16x32_bf16 v[88:91], v[168:171], v[218:221], v[88:91]
	v_mfma_f32_16x16x32_bf16 v[76:79], v[160:163], v[226:229], v[76:79]
	v_mfma_f32_16x16x32_bf16 v[72:75], v[168:171], v[226:229], v[72:75]
	v_mfma_f32_16x16x32_bf16 v[118:121], v[172:175], v[188:191], v[118:121]
	v_mfma_f32_16x16x32_bf16 v[114:117], v[180:183], v[188:191], v[114:117]
	v_mfma_f32_16x16x32_bf16 v[102:105], v[172:175], v[196:199], v[102:105]
	v_mfma_f32_16x16x32_bf16 v[98:101], v[180:183], v[196:199], v[98:101]
	v_mfma_f32_16x16x32_bf16 v[84:87], v[172:175], v[204:207], v[84:87]
	v_mfma_f32_16x16x32_bf16 v[80:83], v[180:183], v[204:207], v[80:83]
	v_mfma_f32_16x16x32_bf16 v[68:71], v[172:175], v[222:225], v[68:71]
	v_mfma_f32_16x16x32_bf16 v[64:67], v[180:183], v[222:225], v[64:67]
	v_mfma_f32_16x16x32_bf16 v[118:121], v[176:179], v[192:195], v[118:121]
	v_mfma_f32_16x16x32_bf16 v[114:117], v[184:187], v[192:195], v[114:117]
	v_mfma_f32_16x16x32_bf16 v[102:105], v[176:179], v[200:203], v[102:105]
	v_mfma_f32_16x16x32_bf16 v[98:101], v[184:187], v[200:203], v[98:101]
	v_mfma_f32_16x16x32_bf16 v[84:87], v[176:179], v[218:221], v[84:87]
	v_mfma_f32_16x16x32_bf16 v[80:83], v[184:187], v[218:221], v[80:83]
	v_mfma_f32_16x16x32_bf16 v[68:71], v[176:179], v[226:229], v[68:71]
	v_mfma_f32_16x16x32_bf16 v[64:67], v[184:187], v[226:229], v[64:67]
	s_barrier
	s_add_i32 s72, s72, s9
	v_lshl_add_u64 v[208:209], s[70:71], 0, v[210:211]
	s_mov_b32 m0, s72
	ds_read_b128 v[188:191], v143 offset:16384
	ds_read_b128 v[192:195], v143 offset:17408
	ds_read_b128 v[196:199], v143 offset:18432
	ds_read_b128 v[200:203], v143 offset:19456
	ds_read_b128 v[204:207], v143 offset:20480
	ds_read_b128 v[218:221], v143 offset:21504
	ds_read_b128 v[222:225], v143 offset:22528
	ds_read_b128 v[226:229], v143 offset:23552
	global_load_lds_dwordx4 v[208:209], off
	s_add_i32 m0, s72, 0x2000
	v_lshl_add_u64 v[230:231], s[70:71], 0, v[130:131]
	s_add_u32 s70, s70, s10
	s_addc_u32 s71, s71, s11
	s_add_i32 s69, s69, s9
	global_load_lds_dwordx4 v[230:231], off
	v_lshl_add_u64 v[232:233], s[70:71], 0, v[210:211]
	s_mov_b32 m0, s69
	v_lshl_add_u64 v[242:243], s[70:71], 0, v[130:131]
	global_load_lds_dwordx4 v[232:233], off
	s_add_i32 m0, s69, 0x2000
	v_lshl_add_u64 v[244:245], s[6:7], 0, v[134:135]
	global_load_lds_dwordx4 v[242:243], off
	s_mov_b32 m0, s13
	v_lshl_add_u64 v[246:247], s[6:7], 0, v[132:133]
	global_load_lds_dwordx4 v[244:245], off
	s_mov_b32 m0, s25
	s_nop 0
	global_load_lds_dwordx4 v[246:247], off
	s_waitcnt vmcnt(8)
	s_waitcnt lgkmcnt(0)
	s_barrier
; #define PG8_STAGE(bufoff, gbase, voff) do { _Pragma("unroll") for (int _i = 0; _i < 2; ++_i) \
;         __builtin_amdgcn_global_load_lds((const unsigned*)((const char*)(gbase) + (voff)[_i]), (PG8_LAS unsigned*)(lds + (bufoff) + ldsw + _i * 8192), 16, 0, 0); } while (0)
; #define PG8_LDA(dst, b, h) do { _Pragma("unroll") for (int m = 0; m < 4; ++m) _Pragma("unroll") for (int k = 0; k < 2; ++k) dst[m][k] = *(const PG8_LAS bf16x8*)(lds + PG8_SA(b, h) + aoff + m * 2048 + k * 1024); } while (0)
; #define PG8_LDB(dst, b, h) do { _Pragma("unroll") for (int n = 0; n < 2; ++n) _Pragma("unroll") for (int k = 0; k < 2; ++k) dst[n][k] = *(const PG8_LAS bf16x8*)(lds + PG8_SB(b, h) + boff + n * 2048 + k * 1024); } while (0)
; #define PG8_MMA(ai, bj, At, Bt) do { __builtin_amdgcn_s_setprio(1); _Pragma("unroll") for (int m = 0; m < 4; ++m) _Pragma("unroll") for (int n = 0; n < 2; ++n) _Pragma("unroll") for (int k = 0; k < 2; ++k) \
;         acc[ai][bj][m][n] = __builtin_amdgcn_mfma_f32_16x16x32_bf16(Bt[n][k], At[m][k], acc[ai][bj][m][n], 0, 0, 0); __builtin_amdgcn_s_setprio(0); } while (0)
; #define PG8_WAIT_V(n) asm volatile("s_waitcnt vmcnt(" #n ")" ::: "memory")
; #define PG8_WAIT_L(n) asm volatile("s_waitcnt lgkmcnt(" #n ")" ::: "memory")
; #define PG8_BAR __builtin_amdgcn_s_barrier()
; #define PG8_SCHED __builtin_amdgcn_sched_barrier(0)
; template <class Epi>
; __device__ __forceinline__ void gemm_phase(PG8_LAS unsigned char* lds, const Gemm g, const StaticOrder& S, const Epi& E, const int wave_s) {
;     ...
;             PG8_WAIT_V(8); PG8_WAIT_L(0); PG8_BAR; PG8_MMA(1, 0, At, B0); PG8_MMA(1, 1, At, B1); PG8_BAR; PG8_SCHED;
;             PG8_LDB(B0, 1, 0); PG8_LDB(B1, 1, 1); PG8_SCHED; PG8_LDA(At, 1, 0); PG8_STAGE(PG8_SA(0, 1), a2 + hstepA, voffA);
;             PG8_WAIT_V(8); PG8_WAIT_L(0); PG8_BAR; PG8_MMA(0, 0, At, B0); PG8_MMA(0, 1, At, B1); PG8_BAR; PG8_SCHED;
	s_waitcnt lgkmcnt(0)
	v_mfma_f32_16x16x32_bf16 v[60:63], v[156:159], v[188:191], v[60:63]
	v_mfma_f32_16x16x32_bf16 v[56:59], v[164:167], v[188:191], v[56:59]
	v_mfma_f32_16x16x32_bf16 v[44:47], v[156:159], v[196:199], v[44:47]
	v_mfma_f32_16x16x32_bf16 v[40:43], v[164:167], v[196:199], v[40:43]
	v_mfma_f32_16x16x32_bf16 v[28:31], v[156:159], v[204:207], v[28:31]
	v_mfma_f32_16x16x32_bf16 v[24:27], v[164:167], v[204:207], v[24:27]
	v_mfma_f32_16x16x32_bf16 v[12:15], v[156:159], v[222:225], v[12:15]
	v_mfma_f32_16x16x32_bf16 v[8:11], v[164:167], v[222:225], v[8:11]
	v_mfma_f32_16x16x32_bf16 v[60:63], v[160:163], v[192:195], v[60:63]
	v_mfma_f32_16x16x32_bf16 v[56:59], v[168:171], v[192:195], v[56:59]
	v_mfma_f32_16x16x32_bf16 v[44:47], v[160:163], v[200:203], v[44:47]
	v_mfma_f32_16x16x32_bf16 v[40:43], v[168:171], v[200:203], v[40:43]
	v_mfma_f32_16x16x32_bf16 v[28:31], v[160:163], v[218:221], v[28:31]
	v_mfma_f32_16x16x32_bf16 v[24:27], v[168:171], v[218:221], v[24:27]
	v_mfma_f32_16x16x32_bf16 v[12:15], v[160:163], v[226:229], v[12:15]
	v_mfma_f32_16x16x32_bf16 v[8:11], v[168:171], v[226:229], v[8:11]
	v_mfma_f32_16x16x32_bf16 v[52:55], v[172:175], v[188:191], v[52:55]
	v_mfma_f32_16x16x32_bf16 v[48:51], v[180:183], v[188:191], v[48:51]
	v_mfma_f32_16x16x32_bf16 v[36:39], v[172:175], v[196:199], v[36:39]
	v_mfma_f32_16x16x32_bf16 v[32:35], v[180:183], v[196:199], v[32:35]
	v_mfma_f32_16x16x32_bf16 v[20:23], v[172:175], v[204:207], v[20:23]
	v_mfma_f32_16x16x32_bf16 v[16:19], v[180:183], v[204:207], v[16:19]
	v_mfma_f32_16x16x32_bf16 v[4:7], v[172:175], v[222:225], v[4:7]
	v_mfma_f32_16x16x32_bf16 v[0:3], v[180:183], v[222:225], v[0:3]
	v_mfma_f32_16x16x32_bf16 v[52:55], v[176:179], v[192:195], v[52:55]
	v_mfma_f32_16x16x32_bf16 v[48:51], v[184:187], v[192:195], v[48:51]
	v_mfma_f32_16x16x32_bf16 v[36:39], v[176:179], v[200:203], v[36:39]
	v_mfma_f32_16x16x32_bf16 v[32:35], v[184:187], v[200:203], v[32:35]
	v_mfma_f32_16x16x32_bf16 v[20:23], v[176:179], v[218:221], v[20:23]
	v_mfma_f32_16x16x32_bf16 v[16:19], v[184:187], v[218:221], v[16:19]
	v_mfma_f32_16x16x32_bf16 v[4:7], v[176:179], v[226:229], v[4:7]
	v_mfma_f32_16x16x32_bf16 v[0:3], v[184:187], v[226:229], v[0:3]
	s_barrier
	s_add_i32 s69, 0, 0x18000
	v_add_u32_e32 v145, s69, v141
	s_add_i32 s70, 0, 0x1c000
	ds_read_b128 v[156:159], v145
	ds_read_b128 v[160:163], v145 offset:1024
	ds_read_b128 v[164:167], v145 offset:2048
	ds_read_b128 v[168:171], v145 offset:3072
	v_add_u32_e32 v145, s70, v141
	ds_read_b128 v[172:175], v145
	ds_read_b128 v[176:179], v145 offset:1024
	ds_read_b128 v[180:183], v145 offset:2048
	ds_read_b128 v[184:187], v145 offset:3072
	s_add_u32 s6, s6, s4
	s_addc_u32 s7, s7, s5
	s_mov_b32 m0, s27
	v_lshl_add_u64 v[248:249], s[6:7], 0, v[134:135]
	ds_read_b128 v[188:191], v143 offset:32768
	ds_read_b128 v[192:195], v143 offset:33792
	ds_read_b128 v[196:199], v143 offset:34816
	ds_read_b128 v[200:203], v143 offset:35840
	ds_read_b128 v[204:207], v143 offset:36864
	ds_read_b128 v[218:221], v143 offset:37888
	ds_read_b128 v[222:225], v143 offset:38912
	ds_read_b128 v[226:229], v143 offset:39936
	global_load_lds_dwordx4 v[248:249], off
	v_lshl_add_u64 v[248:249], s[6:7], 0, v[132:133]
	s_mov_b32 m0, s38
	s_nop 0
	global_load_lds_dwordx4 v[248:249], off
	s_waitcnt vmcnt(8)
	s_waitcnt lgkmcnt(0)
	s_barrier
	s_waitcnt lgkmcnt(0)
	v_mfma_f32_16x16x32_bf16 v[126:129], v[156:159], v[188:191], v[126:129]
	v_mfma_f32_16x16x32_bf16 v[122:125], v[164:167], v[188:191], v[122:125]
	v_mfma_f32_16x16x32_bf16 v[110:113], v[156:159], v[196:199], v[110:113]
	v_mfma_f32_16x16x32_bf16 v[106:109], v[164:167], v[196:199], v[106:109]
	v_mfma_f32_16x16x32_bf16 v[92:95], v[156:159], v[204:207], v[92:95]
	v_mfma_f32_16x16x32_bf16 v[88:91], v[164:167], v[204:207], v[88:91]
	v_mfma_f32_16x16x32_bf16 v[76:79], v[156:159], v[222:225], v[76:79]
	v_mfma_f32_16x16x32_bf16 v[72:75], v[164:167], v[222:225], v[72:75]
	v_mfma_f32_16x16x32_bf16 v[126:129], v[160:163], v[192:195], v[126:129]
	v_mfma_f32_16x16x32_bf16 v[122:125], v[168:171], v[192:195], v[122:125]
	v_mfma_f32_16x16x32_bf16 v[110:113], v[160:163], v[200:203], v[110:113]
	v_mfma_f32_16x16x32_bf16 v[106:109], v[168:171], v[200:203], v[106:109]
	v_mfma_f32_16x16x32_bf16 v[92:95], v[160:163], v[218:221], v[92:95]
	v_mfma_f32_16x16x32_bf16 v[88:91], v[168:171], v[218:221], v[88:91]
	v_mfma_f32_16x16x32_bf16 v[76:79], v[160:163], v[226:229], v[76:79]
	v_mfma_f32_16x16x32_bf16 v[72:75], v[168:171], v[226:229], v[72:75]
	v_mfma_f32_16x16x32_bf16 v[118:121], v[172:175], v[188:191], v[118:121]
	v_mfma_f32_16x16x32_bf16 v[114:117], v[180:183], v[188:191], v[114:117]
	v_mfma_f32_16x16x32_bf16 v[102:105], v[172:175], v[196:199], v[102:105]
	v_mfma_f32_16x16x32_bf16 v[98:101], v[180:183], v[196:199], v[98:101]
	v_mfma_f32_16x16x32_bf16 v[84:87], v[172:175], v[204:207], v[84:87]
	v_mfma_f32_16x16x32_bf16 v[80:83], v[180:183], v[204:207], v[80:83]
	v_mfma_f32_16x16x32_bf16 v[68:71], v[172:175], v[222:225], v[68:71]
	v_mfma_f32_16x16x32_bf16 v[64:67], v[180:183], v[222:225], v[64:67]
	v_mfma_f32_16x16x32_bf16 v[118:121], v[176:179], v[192:195], v[118:121]
	v_mfma_f32_16x16x32_bf16 v[114:117], v[184:187], v[192:195], v[114:117]
	v_mfma_f32_16x16x32_bf16 v[102:105], v[176:179], v[200:203], v[102:105]
	v_mfma_f32_16x16x32_bf16 v[98:101], v[184:187], v[200:203], v[98:101]
	v_mfma_f32_16x16x32_bf16 v[84:87], v[176:179], v[218:221], v[84:87]
	v_mfma_f32_16x16x32_bf16 v[80:83], v[184:187], v[218:221], v[80:83]
	v_mfma_f32_16x16x32_bf16 v[68:71], v[176:179], v[226:229], v[68:71]
	v_mfma_f32_16x16x32_bf16 v[64:67], v[184:187], v[226:229], v[64:67]
	s_barrier
; #define PG8_STAGE(bufoff, gbase, voff) do { _Pragma("unroll") for (int _i = 0; _i < 2; ++_i) \
;         __builtin_amdgcn_global_load_lds((const unsigned*)((const char*)(gbase) + (voff)[_i]), (PG8_LAS unsigned*)(lds + (bufoff) + ldsw + _i * 8192), 16, 0, 0); } while (0)
; #define PG8_LDA(dst, b, h) do { _Pragma("unroll") for (int m = 0; m < 4; ++m) _Pragma("unroll") for (int k = 0; k < 2; ++k) dst[m][k] = *(const PG8_LAS bf16x8*)(lds + PG8_SA(b, h) + aoff + m * 2048 + k * 1024); } while (0)
; #define PG8_MMA(ai, bj, At, Bt) do { __builtin_amdgcn_s_setprio(1); _Pragma("unroll") for (int m = 0; m < 4; ++m) _Pragma("unroll") for (int n = 0; n < 2; ++n) _Pragma("unroll") for (int k = 0; k < 2; ++k) \
;         acc[ai][bj][m][n] = __builtin_amdgcn_mfma_f32_16x16x32_bf16(Bt[n][k], At[m][k], acc[ai][bj][m][n], 0, 0, 0); __builtin_amdgcn_s_setprio(0); } while (0)
; #define PG8_WAIT_V(n) asm volatile("s_waitcnt vmcnt(" #n ")" ::: "memory")
; #define PG8_WAIT_L(n) asm volatile("s_waitcnt lgkmcnt(" #n ")" ::: "memory")
; #define PG8_BAR __builtin_amdgcn_s_barrier()
; #define PG8_SCHED __builtin_amdgcn_sched_barrier(0)
; template <class Epi>
; __device__ __forceinline__ void gemm_phase(PG8_LAS unsigned char* lds, const Gemm g, const StaticOrder& S, const Epi& E, const int wave_s) {
;     ...
;             PG8_LDA(At, 1, 1); PG8_STAGE(PG8_SB(1, 0), b3, voffB); PG8_STAGE(PG8_SB(1, 1), b3 + hstepB, voffB); PG8_STAGE(PG8_SA(1, 0), a3, voffA);
;             PG8_WAIT_V(8); PG8_WAIT_L(0); PG8_BAR; PG8_MMA(1, 0, At, B0); PG8_MMA(1, 1, At, B1); PG8_BAR; PG8_SCHED;
;         }
	s_add_i32 s6, s69, s9
	v_lshl_add_u64 v[208:209], v[208:209], 0, s[52:53]
	s_mov_b32 m0, s6
	ds_read_b128 v[188:191], v143 offset:49152
	ds_read_b128 v[192:195], v143 offset:50176
	ds_read_b128 v[196:199], v143 offset:51200
	ds_read_b128 v[200:203], v143 offset:52224
	ds_read_b128 v[204:207], v143 offset:53248
	ds_read_b128 v[218:221], v143 offset:54272
	ds_read_b128 v[222:225], v143 offset:55296
	ds_read_b128 v[226:229], v143 offset:56320
	global_load_lds_dwordx4 v[208:209], off
	v_lshl_add_u64 v[208:209], v[230:231], 0, s[52:53]
	s_add_i32 m0, s6, 0x2000
	s_add_i32 s6, s70, s9
	global_load_lds_dwordx4 v[208:209], off
	v_lshl_add_u64 v[208:209], v[232:233], 0, s[52:53]
	s_mov_b32 m0, s6
	s_nop 0
	global_load_lds_dwordx4 v[208:209], off
	v_lshl_add_u64 v[208:209], v[242:243], 0, s[52:53]
	s_add_i32 m0, s6, 0x2000
	s_nop 0
	global_load_lds_dwordx4 v[208:209], off
	v_lshl_add_u64 v[208:209], v[244:245], 0, s[52:53]
	s_mov_b32 m0, s39
	s_nop 0
	global_load_lds_dwordx4 v[208:209], off
	v_lshl_add_u64 v[208:209], v[246:247], 0, s[52:53]
	s_mov_b32 m0, s58
	s_nop 0
	global_load_lds_dwordx4 v[208:209], off
	s_waitcnt vmcnt(8)
	s_waitcnt lgkmcnt(0)
	s_barrier
	s_waitcnt lgkmcnt(0)
	v_mfma_f32_16x16x32_bf16 v[60:63], v[156:159], v[188:191], v[60:63]
	v_mfma_f32_16x16x32_bf16 v[56:59], v[164:167], v[188:191], v[56:59]
	s_add_u32 s56, s56, 0x100
	s_addc_u32 s57, s57, 0
	s_add_u32 s66, s66, 0x100
	s_addc_u32 s67, s67, 0
	s_mov_b32 s6, s68
	s_cmp_ge_i32 s68, s59
	v_mfma_f32_16x16x32_bf16 v[44:47], v[156:159], v[196:199], v[44:47]
	v_mfma_f32_16x16x32_bf16 v[40:43], v[164:167], v[196:199], v[40:43]
	v_mfma_f32_16x16x32_bf16 v[28:31], v[156:159], v[204:207], v[28:31]
	v_mfma_f32_16x16x32_bf16 v[24:27], v[164:167], v[204:207], v[24:27]
	v_mfma_f32_16x16x32_bf16 v[12:15], v[156:159], v[222:225], v[12:15]
	v_mfma_f32_16x16x32_bf16 v[8:11], v[164:167], v[222:225], v[8:11]
	v_mfma_f32_16x16x32_bf16 v[60:63], v[160:163], v[192:195], v[60:63]
	v_mfma_f32_16x16x32_bf16 v[56:59], v[168:171], v[192:195], v[56:59]
	v_mfma_f32_16x16x32_bf16 v[44:47], v[160:163], v[200:203], v[44:47]
	v_mfma_f32_16x16x32_bf16 v[40:43], v[168:171], v[200:203], v[40:43]
	v_mfma_f32_16x16x32_bf16 v[28:31], v[160:163], v[218:221], v[28:31]
	v_mfma_f32_16x16x32_bf16 v[24:27], v[168:171], v[218:221], v[24:27]
	v_mfma_f32_16x16x32_bf16 v[12:15], v[160:163], v[226:229], v[12:15]
	v_mfma_f32_16x16x32_bf16 v[8:11], v[168:171], v[226:229], v[8:11]
	v_mfma_f32_16x16x32_bf16 v[52:55], v[172:175], v[188:191], v[52:55]
	v_mfma_f32_16x16x32_bf16 v[48:51], v[180:183], v[188:191], v[48:51]
	v_mfma_f32_16x16x32_bf16 v[36:39], v[172:175], v[196:199], v[36:39]
	v_mfma_f32_16x16x32_bf16 v[32:35], v[180:183], v[196:199], v[32:35]
	v_mfma_f32_16x16x32_bf16 v[20:23], v[172:175], v[204:207], v[20:23]
	v_mfma_f32_16x16x32_bf16 v[16:19], v[180:183], v[204:207], v[16:19]
	v_mfma_f32_16x16x32_bf16 v[4:7], v[172:175], v[222:225], v[4:7]
	v_mfma_f32_16x16x32_bf16 v[0:3], v[180:183], v[222:225], v[0:3]
	v_mfma_f32_16x16x32_bf16 v[52:55], v[176:179], v[192:195], v[52:55]
	v_mfma_f32_16x16x32_bf16 v[48:51], v[184:187], v[192:195], v[48:51]
	v_mfma_f32_16x16x32_bf16 v[36:39], v[176:179], v[200:203], v[36:39]
	v_mfma_f32_16x16x32_bf16 v[32:35], v[184:187], v[200:203], v[32:35]
	v_mfma_f32_16x16x32_bf16 v[20:23], v[176:179], v[218:221], v[20:23]
	v_mfma_f32_16x16x32_bf16 v[16:19], v[184:187], v[218:221], v[16:19]
	v_mfma_f32_16x16x32_bf16 v[4:7], v[176:179], v[226:229], v[4:7]
	v_mfma_f32_16x16x32_bf16 v[0:3], v[184:187], v[226:229], v[0:3]
	s_barrier
	s_cbranch_scc0 .LBB0_950
